# phase0b: with w_down transposes deferred, item indices compacted so no wave does more than 3 transposes (was 4)
# speedup vs baseline: 1.0074x; 1.0062x over previous
.LBB0_66:
	s_add_i32 s61, s61, s71
	s_add_i32 s14, s14, s15
	s_add_i32 s16, s16, s17
	s_add_i32 s18, s18, s19
	s_cmpk_lg_i32 s76, 0x100
	s_cbranch_scc1 .Lp0b_nocomp
	s_cmpk_gt_i32 s61, 0x17ff
	s_cbranch_scc1 .LBB0_154
	s_cmpk_lt_i32 s61, 0x1390
	s_cbranch_scc1 .Lp0b_nocomp
	s_addk_i32 s61, 0x580
	s_add_i32 s14, s14, 0xb000
	s_addk_i32 s16, 0x2c00
	s_addk_i32 s18, 0xb00
.Lp0b_nocomp:
	s_cmpk_gt_i32 s61, 0x1b0f
	s_cbranch_scc1 .LBB0_154

.LBB0_275:
	s_or_b64 exec, exec, s[2:3]
	s_add_i32 s3, 0, 0x23fa8
	s_mov_b32 s2, -1
	v_mov_b32_e32 v0, s3
	s_barrier
	ds_read_b64 v[0:1], v0
	v_mbcnt_lo_u32_b32 v4, s2, 0
	v_mbcnt_hi_u32_b32 v4, s2, v4
	s_waitcnt lgkmcnt(0)
	v_readfirstlane_b32 s11, v0
	v_readfirstlane_b32 s20, v1
	s_add_u32 s21, s11, 0x4800000
	s_addc_u32 s24, s20, 0
	s_add_i32 s3, 0, 0x23f10
	v_mov_b32_e32 v0, s3
	s_add_i32 s3, 0, 0x23f48
	ds_read_b64 v[6:7], v0
	v_mov_b32_e32 v0, s3
	ds_read2_b64 v[0:3], v0 offset1:1
	s_andn2_b64 vcc, exec, s[0:1]
	s_waitcnt lgkmcnt(1)
	v_readfirstlane_b32 s25, v6
	v_readfirstlane_b32 s26, v7
	s_waitcnt lgkmcnt(0)
	v_readfirstlane_b32 s2, v0
	v_cndmask_b32_e64 v0, 0, 1, s[0:1]
	v_cmp_ne_u32_e64 s[6:7], 1, v0
	v_readfirstlane_b32 s3, v1
	v_mov_b32_e32 v1, 0
	v_readfirstlane_b32 s4, v2
	v_readfirstlane_b32 s5, v3
	v_writelane_b32 v247, s6, 12
	v_lshlrev_b32_e32 v0, 1, v4
	s_nop 0
	v_writelane_b32 v247, s7, 13
	s_cbranch_vccnz .LBB0_278
	s_cmpk_lg_i32 s76, 0x100
	s_cbranch_scc1 .Lnsp_generic
	s_mul_i32 s16, s84, 0x1c00
	s_add_u32 s0, s11, s16
	s_addc_u32 s1, s20, 0
	s_add_u32 s0, s0, 0x4801000
	s_addc_u32 s1, s1, 0
	s_lshl_b32 s16, s84, 7
	s_add_u32 s12, s11, s16
	s_addc_u32 s13, s20, 0
	s_add_u32 s6, s12, 0xb800000
	s_addc_u32 s7, s13, 0
	s_lshl_b32 s16, s84, 2
	s_add_u32 s14, s25, s16
	s_addc_u32 s15, s26, 0
	s_mov_b32 s10, 0x3c800000
	v_and_b32_e32 v9, 7, v4
	v_lshlrev_b32_e32 v5, 4, v4
	v_lshrrev_b32_e32 v13, 3, v4
	v_lshlrev_b32_e32 v7, 18, v13
	v_lshl_add_u32 v7, v9, 4, v7
	v_lshlrev_b32_e32 v14, 13, v13
	global_load_dword v11, v14, s[14:15]
	v_lshlrev_b32_e32 v14, 5, v9
	global_load_dwordx4 v[16:19], v14, s[2:3]
	global_load_dwordx4 v[20:23], v14, s[2:3] offset:16
	v_lshrrev_b32_e32 v8, 4, v4
	v_add_u32_e32 v10, -1, v8
	v_max_i32_e32 v10, 0, v10
	v_lshl_add_u32 v10, v10, 8, v14
	global_load_dwordx4 v[24:27], v10, s[4:5]
	global_load_dwordx4 v[28:31], v10, s[4:5] offset:16
	v_cmp_lt_u32_e64 s[16:17], 47, v4
	v_add_u32_e32 v6, 0x400, v5
	v_add_u32_e32 v14, 0x500, v5
	s_nop 0
	v_cndmask_b32_e64 v6, v6, v14, s[16:17]
	global_load_dwordx4 v[48:51], v5, s[0:1]
	global_load_dwordx4 v[52:55], v6, s[0:1]
	s_add_u32 s0, s0, 0xe00000
	s_addc_u32 s1, s1, 0
	global_load_dwordx4 v[56:59], v5, s[0:1]
	global_load_dwordx4 v[60:63], v6, s[0:1]
	s_add_u32 s0, s0, 0xe00000
	s_addc_u32 s1, s1, 0
	global_load_dwordx4 v[64:67], v5, s[0:1]
	global_load_dwordx4 v[68:71], v6, s[0:1]
	s_add_u32 s0, s0, 0xe00000
	s_addc_u32 s1, s1, 0
	global_load_dwordx4 v[72:75], v5, s[0:1]
	global_load_dwordx4 v[76:79], v6, s[0:1]
	s_add_u32 s0, s0, 0xe00000
	s_addc_u32 s1, s1, 0
	global_load_dwordx4 v[80:83], v5, s[0:1]
	global_load_dwordx4 v[84:87], v6, s[0:1]
	s_add_u32 s0, s0, 0xe00000
	s_addc_u32 s1, s1, 0
	global_load_dwordx4 v[88:91], v5, s[0:1]
	global_load_dwordx4 v[92:95], v6, s[0:1]
	s_add_u32 s0, s0, 0xe00000
	s_addc_u32 s1, s1, 0
	global_load_dwordx4 v[96:99], v5, s[0:1]
	global_load_dwordx4 v[100:103], v6, s[0:1]
	s_add_u32 s0, s0, 0xe00000
	s_addc_u32 s1, s1, 0
	global_load_dwordx4 v[104:107], v5, s[0:1]
	global_load_dwordx4 v[108:111], v6, s[0:1]
	s_add_u32 s0, s0, 0xe00000
	s_addc_u32 s1, s1, 0
	v_cmp_eq_u32_e64 s[16:17], 3, v8
	v_mul_u32_u24_e32 v14, 5, v8
	v_add_u32_e32 v14, 0xc8, v14
	v_cndmask_b32_e64 v10, 0, 5, s[16:17]
	v_add_u32_e32 v14, v14, v10
	v_lshlrev_b32_e32 v14, 20, v14
	v_and_b32_e32 v13, 1, v13
	v_lshl_add_u32 v14, v13, 18, v14
	v_cmp_eq_u32_e64 s[18:19], 1, v8
	v_lshl_add_u32 v8, v9, 4, v14
	v_cmp_eq_u32_e64 s[16:17], 0, v9
	v_mov_b32_e32 v10, 0
	v_mov_b32_e32 v15, 0x358637bd
	v_cndmask_b32_e64 v10, v10, -1.0, s[16:17]
	v_cmp_eq_u32_e64 s[16:17], 1, v9
	s_nop 1
	v_cndmask_b32_e64 v10, v10, 1.0, s[16:17]
	v_mov_b32_e32 v13, 1.0
	v_cmp_eq_u32_e32 vcc, 1, v9
	v_mov_b32_e32 v14, 0x3e4693af
	s_nop 0
	v_cndmask_b32_e32 v13, v13, v14, vcc
	v_cmp_eq_u32_e32 vcc, 2, v9
	v_mov_b32_e32 v14, 0x3d1a08c8
	s_nop 0
	v_cndmask_b32_e32 v13, v13, v14, vcc
	v_cmp_eq_u32_e32 vcc, 3, v9
	v_mov_b32_e32 v14, 0x3beef74e
	s_nop 0
	v_cndmask_b32_e32 v13, v13, v14, vcc
	v_cmp_eq_u32_e32 vcc, 4, v9
	v_mov_b32_e32 v14, 0x3ab95d22
	s_nop 0
	v_cndmask_b32_e32 v13, v13, v14, vcc
	v_cmp_eq_u32_e32 vcc, 5, v9
	v_mov_b32_e32 v14, 0x398fc8f8
	s_nop 0
	v_cndmask_b32_e32 v13, v13, v14, vcc
	v_cmp_eq_u32_e32 vcc, 6, v9
	v_mov_b32_e32 v14, 0x385f10c4
	s_nop 0
	v_cndmask_b32_e32 v13, v13, v14, vcc
	v_cmp_eq_u32_e32 vcc, 7, v9
	v_mov_b32_e32 v14, 0x372d07a7
	s_nop 0
	v_cndmask_b32_e32 v13, v13, v14, vcc
	s_waitcnt vmcnt(20)
	v_cvt_f32_i32_e32 v11, v11
	v_mul_f32_e32 v11, v13, v11
	v_mul_f32_e32 v14, 0.15915494, v11
	v_floor_f32_e32 v14, v14
	v_fma_f32 v14, v11, 0.15915494, -v14
	v_cos_f32_e32 v11, v14
	v_sin_f32_e32 v12, v14
	v_cmp_gt_u32_e32 vcc, 2, v9
	s_waitcnt vmcnt(16)
	s_waitcnt vmcnt(14)
	v_readlane_b32 s28, v11, 0
	v_readlane_b32 s38, v12, 0
	v_readlane_b32 s29, v11, 1
	v_readlane_b32 s39, v12, 1
	v_readlane_b32 s30, v11, 2
	v_readlane_b32 s40, v12, 2
	v_readlane_b32 s31, v11, 3
	v_readlane_b32 s41, v12, 3
	v_readlane_b32 s34, v11, 4
	v_readlane_b32 s42, v12, 4
	v_readlane_b32 s35, v11, 5
	v_readlane_b32 s43, v12, 5
	v_readlane_b32 s36, v11, 6
	v_readlane_b32 s44, v12, 6
	v_readlane_b32 s37, v11, 7
	v_readlane_b32 s45, v12, 7
	v_mul_f32_e32 v32, s38, v10
	v_mul_f32_e32 v33, s39, v10
	v_mul_f32_e32 v34, s40, v10
	v_mul_f32_e32 v35, s41, v10
	v_mul_f32_e32 v36, s42, v10
	v_mul_f32_e32 v37, s43, v10
	v_mul_f32_e32 v38, s44, v10
	v_mul_f32_e32 v39, s45, v10
	v_lshlrev_b32_e32 v112, 16, v48
	v_and_b32_e32 v113, 0xffff0000, v48
	v_lshlrev_b32_e32 v114, 16, v49
	v_and_b32_e32 v115, 0xffff0000, v49
	v_lshlrev_b32_e32 v116, 16, v50
	v_and_b32_e32 v117, 0xffff0000, v50
	v_lshlrev_b32_e32 v118, 16, v51
	v_and_b32_e32 v119, 0xffff0000, v51
	v_mul_f32_e32 v140, v112, v112
	v_mul_f32_e32 v141, v113, v113
	v_fmac_f32_e32 v140, v114, v114
	v_fmac_f32_e32 v141, v115, v115
	v_fmac_f32_e32 v140, v116, v116
	v_fmac_f32_e32 v141, v117, v117
	v_fmac_f32_e32 v140, v118, v118
	v_fmac_f32_e32 v141, v119, v119
	v_add_f32_e32 v140, v140, v141
	s_nop 1
	v_add_f32_dpp v140, v140, v140 quad_perm:[1,0,3,2] row_mask:0xf bank_mask:0xf bound_ctrl:1
	s_nop 1
	v_add_f32_dpp v140, v140, v140 quad_perm:[2,3,0,1] row_mask:0xf bank_mask:0xf bound_ctrl:1
	s_nop 1
	v_add_f32_dpp v140, v140, v140 row_half_mirror row_mask:0xf bank_mask:0xf bound_ctrl:1
	v_fma_f32 v141, v140, s10, v15
	v_rsq_f32_e32 v141, v141
	s_nop 0
	v_mul_f32_e32 v112, v112, v141
	v_mul_f32_e32 v113, v113, v141
	v_mul_f32_e32 v114, v114, v141
	v_mul_f32_e32 v115, v115, v141
	v_mul_f32_e32 v116, v116, v141
	v_mul_f32_e32 v117, v117, v141
	v_mul_f32_e32 v118, v118, v141
	v_mul_f32_e32 v119, v119, v141
	v_mul_f32_e32 v112, v112, v16
	v_mul_f32_e32 v113, v113, v17
	v_mul_f32_e32 v114, v114, v18
	v_mul_f32_e32 v115, v115, v19
	v_mul_f32_e32 v116, v116, v20
	v_mul_f32_e32 v117, v117, v21
	v_mul_f32_e32 v118, v118, v22
	v_mul_f32_e32 v119, v119, v23
	v_mov_b32_dpp v120, v112 quad_perm:[1,0,3,2] row_mask:0xf bank_mask:0xf
	v_mov_b32_dpp v121, v113 quad_perm:[1,0,3,2] row_mask:0xf bank_mask:0xf
	v_mov_b32_dpp v122, v114 quad_perm:[1,0,3,2] row_mask:0xf bank_mask:0xf
	v_mov_b32_dpp v123, v115 quad_perm:[1,0,3,2] row_mask:0xf bank_mask:0xf
	v_mov_b32_dpp v124, v116 quad_perm:[1,0,3,2] row_mask:0xf bank_mask:0xf
	v_mov_b32_dpp v125, v117 quad_perm:[1,0,3,2] row_mask:0xf bank_mask:0xf
	v_mov_b32_dpp v126, v118 quad_perm:[1,0,3,2] row_mask:0xf bank_mask:0xf
	v_mov_b32_dpp v127, v119 quad_perm:[1,0,3,2] row_mask:0xf bank_mask:0xf
	v_mul_f32_e32 v128, s28, v112
	v_mul_f32_e32 v129, s29, v113
	v_mul_f32_e32 v130, s30, v114
	v_mul_f32_e32 v131, s31, v115
	v_mul_f32_e32 v132, s34, v116
	v_mul_f32_e32 v133, s35, v117
	v_mul_f32_e32 v134, s36, v118
	v_mul_f32_e32 v135, s37, v119
	v_fmac_f32_e32 v128, v32, v120
	v_fmac_f32_e32 v129, v33, v121
	v_fmac_f32_e32 v130, v34, v122
	v_fmac_f32_e32 v131, v35, v123
	v_fmac_f32_e32 v132, v36, v124
	v_fmac_f32_e32 v133, v37, v125
	v_fmac_f32_e32 v134, v38, v126
	v_fmac_f32_e32 v135, v39, v127
	v_cndmask_b32_e32 v112, v112, v128, vcc
	v_cndmask_b32_e32 v113, v113, v129, vcc
	v_cndmask_b32_e32 v114, v114, v130, vcc
	v_cndmask_b32_e32 v115, v115, v131, vcc
	v_cndmask_b32_e32 v116, v116, v132, vcc
	v_cndmask_b32_e32 v117, v117, v133, vcc
	v_cndmask_b32_e32 v118, v118, v134, vcc
	v_cndmask_b32_e32 v119, v119, v135, vcc
	v_mul_f32_e32 v112, 0x3e38aa3b, v112
	v_mul_f32_e32 v113, 0x3e38aa3b, v113
	v_mul_f32_e32 v114, 0x3e38aa3b, v114
	v_mul_f32_e32 v115, 0x3e38aa3b, v115
	v_mul_f32_e32 v116, 0x3e38aa3b, v116
	v_mul_f32_e32 v117, 0x3e38aa3b, v117
	v_mul_f32_e32 v118, 0x3e38aa3b, v118
	v_mul_f32_e32 v119, 0x3e38aa3b, v119
	v_cvt_pk_bf16_f32 v136, v112, v113
	v_cvt_pk_bf16_f32 v137, v114, v115
	v_cvt_pk_bf16_f32 v138, v116, v117
	v_cvt_pk_bf16_f32 v139, v118, v119
	global_store_dwordx4 v7, v[136:139], s[6:7]
	s_nop 1
	v_lshlrev_b32_e32 v112, 16, v52
	v_and_b32_e32 v113, 0xffff0000, v52
	v_lshlrev_b32_e32 v114, 16, v53
	v_and_b32_e32 v115, 0xffff0000, v53
	v_lshlrev_b32_e32 v116, 16, v54
	v_and_b32_e32 v117, 0xffff0000, v54
	v_lshlrev_b32_e32 v118, 16, v55
	v_and_b32_e32 v119, 0xffff0000, v55
	v_mul_f32_e32 v140, v112, v112
	v_mul_f32_e32 v141, v113, v113
	v_fmac_f32_e32 v140, v114, v114
	v_fmac_f32_e32 v141, v115, v115
	v_fmac_f32_e32 v140, v116, v116
	v_fmac_f32_e32 v141, v117, v117
	v_fmac_f32_e32 v140, v118, v118
	v_fmac_f32_e32 v141, v119, v119
	v_add_f32_e32 v140, v140, v141
	s_nop 1
	v_add_f32_dpp v140, v140, v140 quad_perm:[1,0,3,2] row_mask:0xf bank_mask:0xf bound_ctrl:1
	s_nop 1
	v_add_f32_dpp v140, v140, v140 quad_perm:[2,3,0,1] row_mask:0xf bank_mask:0xf bound_ctrl:1
	s_nop 1
	v_add_f32_dpp v140, v140, v140 row_half_mirror row_mask:0xf bank_mask:0xf bound_ctrl:1
	v_fma_f32 v141, v140, s10, v15
	v_rsq_f32_e32 v141, v141
	s_nop 0
	v_mul_f32_e32 v112, v112, v141
	v_mul_f32_e32 v113, v113, v141
	v_mul_f32_e32 v114, v114, v141
	v_mul_f32_e32 v115, v115, v141
	v_mul_f32_e32 v116, v116, v141
	v_mul_f32_e32 v117, v117, v141
	v_mul_f32_e32 v118, v118, v141
	v_mul_f32_e32 v119, v119, v141
	v_mul_f32_e32 v112, v112, v24
	v_mul_f32_e32 v113, v113, v25
	v_mul_f32_e32 v114, v114, v26
	v_mul_f32_e32 v115, v115, v27
	v_mul_f32_e32 v116, v116, v28
	v_mul_f32_e32 v117, v117, v29
	v_mul_f32_e32 v118, v118, v30
	v_mul_f32_e32 v119, v119, v31
	v_mov_b32_dpp v120, v112 quad_perm:[1,0,3,2] row_mask:0xf bank_mask:0xf
	v_mov_b32_dpp v121, v113 quad_perm:[1,0,3,2] row_mask:0xf bank_mask:0xf
	v_mov_b32_dpp v122, v114 quad_perm:[1,0,3,2] row_mask:0xf bank_mask:0xf
	v_mov_b32_dpp v123, v115 quad_perm:[1,0,3,2] row_mask:0xf bank_mask:0xf
	v_mov_b32_dpp v124, v116 quad_perm:[1,0,3,2] row_mask:0xf bank_mask:0xf
	v_mov_b32_dpp v125, v117 quad_perm:[1,0,3,2] row_mask:0xf bank_mask:0xf
	v_mov_b32_dpp v126, v118 quad_perm:[1,0,3,2] row_mask:0xf bank_mask:0xf
	v_mov_b32_dpp v127, v119 quad_perm:[1,0,3,2] row_mask:0xf bank_mask:0xf
	v_mul_f32_e32 v128, s28, v112
	v_mul_f32_e32 v129, s29, v113
	v_mul_f32_e32 v130, s30, v114
	v_mul_f32_e32 v131, s31, v115
	v_mul_f32_e32 v132, s34, v116
	v_mul_f32_e32 v133, s35, v117
	v_mul_f32_e32 v134, s36, v118
	v_mul_f32_e32 v135, s37, v119
	v_fmac_f32_e32 v128, v32, v120
	v_fmac_f32_e32 v129, v33, v121
	v_fmac_f32_e32 v130, v34, v122
	v_fmac_f32_e32 v131, v35, v123
	v_fmac_f32_e32 v132, v36, v124
	v_fmac_f32_e32 v133, v37, v125
	v_fmac_f32_e32 v134, v38, v126
	v_fmac_f32_e32 v135, v39, v127
	v_cndmask_b32_e32 v112, v112, v128, vcc
	v_cndmask_b32_e32 v113, v113, v129, vcc
	v_cndmask_b32_e32 v114, v114, v130, vcc
	v_cndmask_b32_e32 v115, v115, v131, vcc
	v_cndmask_b32_e32 v116, v116, v132, vcc
	v_cndmask_b32_e32 v117, v117, v133, vcc
	v_cndmask_b32_e32 v118, v118, v134, vcc
	v_cndmask_b32_e32 v119, v119, v135, vcc
	v_cvt_pk_bf16_f32 v136, v112, v113
	v_cvt_pk_bf16_f32 v137, v114, v115
	v_cvt_pk_bf16_f32 v138, v116, v117
	v_cvt_pk_bf16_f32 v139, v118, v119
	v_cndmask_b32_e64 v136, v136, v52, s[18:19]
	v_cndmask_b32_e64 v137, v137, v53, s[18:19]
	v_cndmask_b32_e64 v138, v138, v54, s[18:19]
	v_cndmask_b32_e64 v139, v139, v55, s[18:19]
	global_store_dwordx4 v8, v[136:139], s[12:13]
	s_add_u32 s6, s6, 0x200000
	s_addc_u32 s7, s7, 0
	s_add_u32 s12, s12, 0x80000
	s_addc_u32 s13, s13, 0
	s_waitcnt vmcnt(14)
	v_readlane_b32 s28, v11, 8
	v_readlane_b32 s38, v12, 8
	v_readlane_b32 s29, v11, 9
	v_readlane_b32 s39, v12, 9
	v_readlane_b32 s30, v11, 10
	v_readlane_b32 s40, v12, 10
	v_readlane_b32 s31, v11, 11
	v_readlane_b32 s41, v12, 11
	v_readlane_b32 s34, v11, 12
	v_readlane_b32 s42, v12, 12
	v_readlane_b32 s35, v11, 13
	v_readlane_b32 s43, v12, 13
	v_readlane_b32 s36, v11, 14
	v_readlane_b32 s44, v12, 14
	v_readlane_b32 s37, v11, 15
	v_readlane_b32 s45, v12, 15
	v_mul_f32_e32 v32, s38, v10
	v_mul_f32_e32 v33, s39, v10
	v_mul_f32_e32 v34, s40, v10
	v_mul_f32_e32 v35, s41, v10
	v_mul_f32_e32 v36, s42, v10
	v_mul_f32_e32 v37, s43, v10
	v_mul_f32_e32 v38, s44, v10
	v_mul_f32_e32 v39, s45, v10
	v_lshlrev_b32_e32 v112, 16, v56
	v_and_b32_e32 v113, 0xffff0000, v56
	v_lshlrev_b32_e32 v114, 16, v57
	v_and_b32_e32 v115, 0xffff0000, v57
	v_lshlrev_b32_e32 v116, 16, v58
	v_and_b32_e32 v117, 0xffff0000, v58
	v_lshlrev_b32_e32 v118, 16, v59
	v_and_b32_e32 v119, 0xffff0000, v59
	v_mul_f32_e32 v140, v112, v112
	v_mul_f32_e32 v141, v113, v113
	v_fmac_f32_e32 v140, v114, v114
	v_fmac_f32_e32 v141, v115, v115
	v_fmac_f32_e32 v140, v116, v116
	v_fmac_f32_e32 v141, v117, v117
	v_fmac_f32_e32 v140, v118, v118
	v_fmac_f32_e32 v141, v119, v119
	v_add_f32_e32 v140, v140, v141
	s_nop 1
	v_add_f32_dpp v140, v140, v140 quad_perm:[1,0,3,2] row_mask:0xf bank_mask:0xf bound_ctrl:1
	s_nop 1
	v_add_f32_dpp v140, v140, v140 quad_perm:[2,3,0,1] row_mask:0xf bank_mask:0xf bound_ctrl:1
	s_nop 1
	v_add_f32_dpp v140, v140, v140 row_half_mirror row_mask:0xf bank_mask:0xf bound_ctrl:1
	v_fma_f32 v141, v140, s10, v15
	v_rsq_f32_e32 v141, v141
	s_nop 0
	v_mul_f32_e32 v112, v112, v141
	v_mul_f32_e32 v113, v113, v141
	v_mul_f32_e32 v114, v114, v141
	v_mul_f32_e32 v115, v115, v141
	v_mul_f32_e32 v116, v116, v141
	v_mul_f32_e32 v117, v117, v141
	v_mul_f32_e32 v118, v118, v141
	v_mul_f32_e32 v119, v119, v141
	v_mul_f32_e32 v112, v112, v16
	v_mul_f32_e32 v113, v113, v17
	v_mul_f32_e32 v114, v114, v18
	v_mul_f32_e32 v115, v115, v19
	v_mul_f32_e32 v116, v116, v20
	v_mul_f32_e32 v117, v117, v21
	v_mul_f32_e32 v118, v118, v22
	v_mul_f32_e32 v119, v119, v23
	v_mov_b32_dpp v120, v112 quad_perm:[1,0,3,2] row_mask:0xf bank_mask:0xf
	v_mov_b32_dpp v121, v113 quad_perm:[1,0,3,2] row_mask:0xf bank_mask:0xf
	v_mov_b32_dpp v122, v114 quad_perm:[1,0,3,2] row_mask:0xf bank_mask:0xf
	v_mov_b32_dpp v123, v115 quad_perm:[1,0,3,2] row_mask:0xf bank_mask:0xf
	v_mov_b32_dpp v124, v116 quad_perm:[1,0,3,2] row_mask:0xf bank_mask:0xf
	v_mov_b32_dpp v125, v117 quad_perm:[1,0,3,2] row_mask:0xf bank_mask:0xf
	v_mov_b32_dpp v126, v118 quad_perm:[1,0,3,2] row_mask:0xf bank_mask:0xf
	v_mov_b32_dpp v127, v119 quad_perm:[1,0,3,2] row_mask:0xf bank_mask:0xf
	v_mul_f32_e32 v128, s28, v112
	v_mul_f32_e32 v129, s29, v113
	v_mul_f32_e32 v130, s30, v114
	v_mul_f32_e32 v131, s31, v115
	v_mul_f32_e32 v132, s34, v116
	v_mul_f32_e32 v133, s35, v117
	v_mul_f32_e32 v134, s36, v118
	v_mul_f32_e32 v135, s37, v119
	v_fmac_f32_e32 v128, v32, v120
	v_fmac_f32_e32 v129, v33, v121
	v_fmac_f32_e32 v130, v34, v122
	v_fmac_f32_e32 v131, v35, v123
	v_fmac_f32_e32 v132, v36, v124
	v_fmac_f32_e32 v133, v37, v125
	v_fmac_f32_e32 v134, v38, v126
	v_fmac_f32_e32 v135, v39, v127
	v_cndmask_b32_e32 v112, v112, v128, vcc
	v_cndmask_b32_e32 v113, v113, v129, vcc
	v_cndmask_b32_e32 v114, v114, v130, vcc
	v_cndmask_b32_e32 v115, v115, v131, vcc
	v_cndmask_b32_e32 v116, v116, v132, vcc
	v_cndmask_b32_e32 v117, v117, v133, vcc
	v_cndmask_b32_e32 v118, v118, v134, vcc
	v_cndmask_b32_e32 v119, v119, v135, vcc
	v_mul_f32_e32 v112, 0x3e38aa3b, v112
	v_mul_f32_e32 v113, 0x3e38aa3b, v113
	v_mul_f32_e32 v114, 0x3e38aa3b, v114
	v_mul_f32_e32 v115, 0x3e38aa3b, v115
	v_mul_f32_e32 v116, 0x3e38aa3b, v116
	v_mul_f32_e32 v117, 0x3e38aa3b, v117
	v_mul_f32_e32 v118, 0x3e38aa3b, v118
	v_mul_f32_e32 v119, 0x3e38aa3b, v119
	v_cvt_pk_bf16_f32 v136, v112, v113
	v_cvt_pk_bf16_f32 v137, v114, v115
	v_cvt_pk_bf16_f32 v138, v116, v117
	v_cvt_pk_bf16_f32 v139, v118, v119
	global_store_dwordx4 v7, v[136:139], s[6:7]
	s_nop 1
	v_lshlrev_b32_e32 v112, 16, v60
	v_and_b32_e32 v113, 0xffff0000, v60
	v_lshlrev_b32_e32 v114, 16, v61
	v_and_b32_e32 v115, 0xffff0000, v61
	v_lshlrev_b32_e32 v116, 16, v62
	v_and_b32_e32 v117, 0xffff0000, v62
	v_lshlrev_b32_e32 v118, 16, v63
	v_and_b32_e32 v119, 0xffff0000, v63
	v_mul_f32_e32 v140, v112, v112
	v_mul_f32_e32 v141, v113, v113
	v_fmac_f32_e32 v140, v114, v114
	v_fmac_f32_e32 v141, v115, v115
	v_fmac_f32_e32 v140, v116, v116
	v_fmac_f32_e32 v141, v117, v117
	v_fmac_f32_e32 v140, v118, v118
	v_fmac_f32_e32 v141, v119, v119
	v_add_f32_e32 v140, v140, v141
	s_nop 1
	v_add_f32_dpp v140, v140, v140 quad_perm:[1,0,3,2] row_mask:0xf bank_mask:0xf bound_ctrl:1
	s_nop 1
	v_add_f32_dpp v140, v140, v140 quad_perm:[2,3,0,1] row_mask:0xf bank_mask:0xf bound_ctrl:1
	s_nop 1
	v_add_f32_dpp v140, v140, v140 row_half_mirror row_mask:0xf bank_mask:0xf bound_ctrl:1
	v_fma_f32 v141, v140, s10, v15
	v_rsq_f32_e32 v141, v141
	s_nop 0
	v_mul_f32_e32 v112, v112, v141
	v_mul_f32_e32 v113, v113, v141
	v_mul_f32_e32 v114, v114, v141
	v_mul_f32_e32 v115, v115, v141
	v_mul_f32_e32 v116, v116, v141
	v_mul_f32_e32 v117, v117, v141
	v_mul_f32_e32 v118, v118, v141
	v_mul_f32_e32 v119, v119, v141
	v_mul_f32_e32 v112, v112, v24
	v_mul_f32_e32 v113, v113, v25
	v_mul_f32_e32 v114, v114, v26
	v_mul_f32_e32 v115, v115, v27
	v_mul_f32_e32 v116, v116, v28
	v_mul_f32_e32 v117, v117, v29
	v_mul_f32_e32 v118, v118, v30
	v_mul_f32_e32 v119, v119, v31
	v_mov_b32_dpp v120, v112 quad_perm:[1,0,3,2] row_mask:0xf bank_mask:0xf
	v_mov_b32_dpp v121, v113 quad_perm:[1,0,3,2] row_mask:0xf bank_mask:0xf
	v_mov_b32_dpp v122, v114 quad_perm:[1,0,3,2] row_mask:0xf bank_mask:0xf
	v_mov_b32_dpp v123, v115 quad_perm:[1,0,3,2] row_mask:0xf bank_mask:0xf
	v_mov_b32_dpp v124, v116 quad_perm:[1,0,3,2] row_mask:0xf bank_mask:0xf
	v_mov_b32_dpp v125, v117 quad_perm:[1,0,3,2] row_mask:0xf bank_mask:0xf
	v_mov_b32_dpp v126, v118 quad_perm:[1,0,3,2] row_mask:0xf bank_mask:0xf
	v_mov_b32_dpp v127, v119 quad_perm:[1,0,3,2] row_mask:0xf bank_mask:0xf
	v_mul_f32_e32 v128, s28, v112
	v_mul_f32_e32 v129, s29, v113
	v_mul_f32_e32 v130, s30, v114
	v_mul_f32_e32 v131, s31, v115
	v_mul_f32_e32 v132, s34, v116
	v_mul_f32_e32 v133, s35, v117
	v_mul_f32_e32 v134, s36, v118
	v_mul_f32_e32 v135, s37, v119
	v_fmac_f32_e32 v128, v32, v120
	v_fmac_f32_e32 v129, v33, v121
	v_fmac_f32_e32 v130, v34, v122
	v_fmac_f32_e32 v131, v35, v123
	v_fmac_f32_e32 v132, v36, v124
	v_fmac_f32_e32 v133, v37, v125
	v_fmac_f32_e32 v134, v38, v126
	v_fmac_f32_e32 v135, v39, v127
	v_cndmask_b32_e32 v112, v112, v128, vcc
	v_cndmask_b32_e32 v113, v113, v129, vcc
	v_cndmask_b32_e32 v114, v114, v130, vcc
	v_cndmask_b32_e32 v115, v115, v131, vcc
	v_cndmask_b32_e32 v116, v116, v132, vcc
	v_cndmask_b32_e32 v117, v117, v133, vcc
	v_cndmask_b32_e32 v118, v118, v134, vcc
	v_cndmask_b32_e32 v119, v119, v135, vcc
	v_cvt_pk_bf16_f32 v136, v112, v113
	v_cvt_pk_bf16_f32 v137, v114, v115
	v_cvt_pk_bf16_f32 v138, v116, v117
	v_cvt_pk_bf16_f32 v139, v118, v119
	v_cndmask_b32_e64 v136, v136, v60, s[18:19]
	v_cndmask_b32_e64 v137, v137, v61, s[18:19]
	v_cndmask_b32_e64 v138, v138, v62, s[18:19]
	v_cndmask_b32_e64 v139, v139, v63, s[18:19]
	global_store_dwordx4 v8, v[136:139], s[12:13]
	s_add_u32 s6, s6, 0x200000
	s_addc_u32 s7, s7, 0
	s_add_u32 s12, s12, 0x80000
	s_addc_u32 s13, s13, 0
	s_waitcnt vmcnt(14)
	v_readlane_b32 s28, v11, 16
	v_readlane_b32 s38, v12, 16
	v_readlane_b32 s29, v11, 17
	v_readlane_b32 s39, v12, 17
	v_readlane_b32 s30, v11, 18
	v_readlane_b32 s40, v12, 18
	v_readlane_b32 s31, v11, 19
	v_readlane_b32 s41, v12, 19
	v_readlane_b32 s34, v11, 20
	v_readlane_b32 s42, v12, 20
	v_readlane_b32 s35, v11, 21
	v_readlane_b32 s43, v12, 21
	v_readlane_b32 s36, v11, 22
	v_readlane_b32 s44, v12, 22
	v_readlane_b32 s37, v11, 23
	v_readlane_b32 s45, v12, 23
	v_mul_f32_e32 v32, s38, v10
	v_mul_f32_e32 v33, s39, v10
	v_mul_f32_e32 v34, s40, v10
	v_mul_f32_e32 v35, s41, v10
	v_mul_f32_e32 v36, s42, v10
	v_mul_f32_e32 v37, s43, v10
	v_mul_f32_e32 v38, s44, v10
	v_mul_f32_e32 v39, s45, v10
	v_lshlrev_b32_e32 v112, 16, v64
	v_and_b32_e32 v113, 0xffff0000, v64
	v_lshlrev_b32_e32 v114, 16, v65
	v_and_b32_e32 v115, 0xffff0000, v65
	v_lshlrev_b32_e32 v116, 16, v66
	v_and_b32_e32 v117, 0xffff0000, v66
	v_lshlrev_b32_e32 v118, 16, v67
	v_and_b32_e32 v119, 0xffff0000, v67
	v_mul_f32_e32 v140, v112, v112
	v_mul_f32_e32 v141, v113, v113
	v_fmac_f32_e32 v140, v114, v114
	v_fmac_f32_e32 v141, v115, v115
	v_fmac_f32_e32 v140, v116, v116
	v_fmac_f32_e32 v141, v117, v117
	v_fmac_f32_e32 v140, v118, v118
	v_fmac_f32_e32 v141, v119, v119
	v_add_f32_e32 v140, v140, v141
	s_nop 1
	v_add_f32_dpp v140, v140, v140 quad_perm:[1,0,3,2] row_mask:0xf bank_mask:0xf bound_ctrl:1
	s_nop 1
	v_add_f32_dpp v140, v140, v140 quad_perm:[2,3,0,1] row_mask:0xf bank_mask:0xf bound_ctrl:1
	s_nop 1
	v_add_f32_dpp v140, v140, v140 row_half_mirror row_mask:0xf bank_mask:0xf bound_ctrl:1
	v_fma_f32 v141, v140, s10, v15
	v_rsq_f32_e32 v141, v141
	s_nop 0
	v_mul_f32_e32 v112, v112, v141
	v_mul_f32_e32 v113, v113, v141
	v_mul_f32_e32 v114, v114, v141
	v_mul_f32_e32 v115, v115, v141
	v_mul_f32_e32 v116, v116, v141
	v_mul_f32_e32 v117, v117, v141
	v_mul_f32_e32 v118, v118, v141
	v_mul_f32_e32 v119, v119, v141
	v_mul_f32_e32 v112, v112, v16
	v_mul_f32_e32 v113, v113, v17
	v_mul_f32_e32 v114, v114, v18
	v_mul_f32_e32 v115, v115, v19
	v_mul_f32_e32 v116, v116, v20
	v_mul_f32_e32 v117, v117, v21
	v_mul_f32_e32 v118, v118, v22
	v_mul_f32_e32 v119, v119, v23
	v_mov_b32_dpp v120, v112 quad_perm:[1,0,3,2] row_mask:0xf bank_mask:0xf
	v_mov_b32_dpp v121, v113 quad_perm:[1,0,3,2] row_mask:0xf bank_mask:0xf
	v_mov_b32_dpp v122, v114 quad_perm:[1,0,3,2] row_mask:0xf bank_mask:0xf
	v_mov_b32_dpp v123, v115 quad_perm:[1,0,3,2] row_mask:0xf bank_mask:0xf
	v_mov_b32_dpp v124, v116 quad_perm:[1,0,3,2] row_mask:0xf bank_mask:0xf
	v_mov_b32_dpp v125, v117 quad_perm:[1,0,3,2] row_mask:0xf bank_mask:0xf
	v_mov_b32_dpp v126, v118 quad_perm:[1,0,3,2] row_mask:0xf bank_mask:0xf
	v_mov_b32_dpp v127, v119 quad_perm:[1,0,3,2] row_mask:0xf bank_mask:0xf
	v_mul_f32_e32 v128, s28, v112
	v_mul_f32_e32 v129, s29, v113
	v_mul_f32_e32 v130, s30, v114
	v_mul_f32_e32 v131, s31, v115
	v_mul_f32_e32 v132, s34, v116
	v_mul_f32_e32 v133, s35, v117
	v_mul_f32_e32 v134, s36, v118
	v_mul_f32_e32 v135, s37, v119
	v_fmac_f32_e32 v128, v32, v120
	v_fmac_f32_e32 v129, v33, v121
	v_fmac_f32_e32 v130, v34, v122
	v_fmac_f32_e32 v131, v35, v123
	v_fmac_f32_e32 v132, v36, v124
	v_fmac_f32_e32 v133, v37, v125
	v_fmac_f32_e32 v134, v38, v126
	v_fmac_f32_e32 v135, v39, v127
	v_cndmask_b32_e32 v112, v112, v128, vcc
	v_cndmask_b32_e32 v113, v113, v129, vcc
	v_cndmask_b32_e32 v114, v114, v130, vcc
	v_cndmask_b32_e32 v115, v115, v131, vcc
	v_cndmask_b32_e32 v116, v116, v132, vcc
	v_cndmask_b32_e32 v117, v117, v133, vcc
	v_cndmask_b32_e32 v118, v118, v134, vcc
	v_cndmask_b32_e32 v119, v119, v135, vcc
	v_mul_f32_e32 v112, 0x3e38aa3b, v112
	v_mul_f32_e32 v113, 0x3e38aa3b, v113
	v_mul_f32_e32 v114, 0x3e38aa3b, v114
	v_mul_f32_e32 v115, 0x3e38aa3b, v115
	v_mul_f32_e32 v116, 0x3e38aa3b, v116
	v_mul_f32_e32 v117, 0x3e38aa3b, v117
	v_mul_f32_e32 v118, 0x3e38aa3b, v118
	v_mul_f32_e32 v119, 0x3e38aa3b, v119
	v_cvt_pk_bf16_f32 v136, v112, v113
	v_cvt_pk_bf16_f32 v137, v114, v115
	v_cvt_pk_bf16_f32 v138, v116, v117
	v_cvt_pk_bf16_f32 v139, v118, v119
	global_store_dwordx4 v7, v[136:139], s[6:7]
	s_nop 1
	v_lshlrev_b32_e32 v112, 16, v68
	v_and_b32_e32 v113, 0xffff0000, v68
	v_lshlrev_b32_e32 v114, 16, v69
	v_and_b32_e32 v115, 0xffff0000, v69
	v_lshlrev_b32_e32 v116, 16, v70
	v_and_b32_e32 v117, 0xffff0000, v70
	v_lshlrev_b32_e32 v118, 16, v71
	v_and_b32_e32 v119, 0xffff0000, v71
	v_mul_f32_e32 v140, v112, v112
	v_mul_f32_e32 v141, v113, v113
	v_fmac_f32_e32 v140, v114, v114
	v_fmac_f32_e32 v141, v115, v115
	v_fmac_f32_e32 v140, v116, v116
	v_fmac_f32_e32 v141, v117, v117
	v_fmac_f32_e32 v140, v118, v118
	v_fmac_f32_e32 v141, v119, v119
	v_add_f32_e32 v140, v140, v141
	s_nop 1
	v_add_f32_dpp v140, v140, v140 quad_perm:[1,0,3,2] row_mask:0xf bank_mask:0xf bound_ctrl:1
	s_nop 1
	v_add_f32_dpp v140, v140, v140 quad_perm:[2,3,0,1] row_mask:0xf bank_mask:0xf bound_ctrl:1
	s_nop 1
	v_add_f32_dpp v140, v140, v140 row_half_mirror row_mask:0xf bank_mask:0xf bound_ctrl:1
	v_fma_f32 v141, v140, s10, v15
	v_rsq_f32_e32 v141, v141
	s_nop 0
	v_mul_f32_e32 v112, v112, v141
	v_mul_f32_e32 v113, v113, v141
	v_mul_f32_e32 v114, v114, v141
	v_mul_f32_e32 v115, v115, v141
	v_mul_f32_e32 v116, v116, v141
	v_mul_f32_e32 v117, v117, v141
	v_mul_f32_e32 v118, v118, v141
	v_mul_f32_e32 v119, v119, v141
	v_mul_f32_e32 v112, v112, v24
	v_mul_f32_e32 v113, v113, v25
	v_mul_f32_e32 v114, v114, v26
	v_mul_f32_e32 v115, v115, v27
	v_mul_f32_e32 v116, v116, v28
	v_mul_f32_e32 v117, v117, v29
	v_mul_f32_e32 v118, v118, v30
	v_mul_f32_e32 v119, v119, v31
	v_mov_b32_dpp v120, v112 quad_perm:[1,0,3,2] row_mask:0xf bank_mask:0xf
	v_mov_b32_dpp v121, v113 quad_perm:[1,0,3,2] row_mask:0xf bank_mask:0xf
	v_mov_b32_dpp v122, v114 quad_perm:[1,0,3,2] row_mask:0xf bank_mask:0xf
	v_mov_b32_dpp v123, v115 quad_perm:[1,0,3,2] row_mask:0xf bank_mask:0xf
	v_mov_b32_dpp v124, v116 quad_perm:[1,0,3,2] row_mask:0xf bank_mask:0xf
	v_mov_b32_dpp v125, v117 quad_perm:[1,0,3,2] row_mask:0xf bank_mask:0xf
	v_mov_b32_dpp v126, v118 quad_perm:[1,0,3,2] row_mask:0xf bank_mask:0xf
	v_mov_b32_dpp v127, v119 quad_perm:[1,0,3,2] row_mask:0xf bank_mask:0xf
	v_mul_f32_e32 v128, s28, v112
	v_mul_f32_e32 v129, s29, v113
	v_mul_f32_e32 v130, s30, v114
	v_mul_f32_e32 v131, s31, v115
	v_mul_f32_e32 v132, s34, v116
	v_mul_f32_e32 v133, s35, v117
	v_mul_f32_e32 v134, s36, v118
	v_mul_f32_e32 v135, s37, v119
	v_fmac_f32_e32 v128, v32, v120
	v_fmac_f32_e32 v129, v33, v121
	v_fmac_f32_e32 v130, v34, v122
	v_fmac_f32_e32 v131, v35, v123
	v_fmac_f32_e32 v132, v36, v124
	v_fmac_f32_e32 v133, v37, v125
	v_fmac_f32_e32 v134, v38, v126
	v_fmac_f32_e32 v135, v39, v127
	v_cndmask_b32_e32 v112, v112, v128, vcc
	v_cndmask_b32_e32 v113, v113, v129, vcc
	v_cndmask_b32_e32 v114, v114, v130, vcc
	v_cndmask_b32_e32 v115, v115, v131, vcc
	v_cndmask_b32_e32 v116, v116, v132, vcc
	v_cndmask_b32_e32 v117, v117, v133, vcc
	v_cndmask_b32_e32 v118, v118, v134, vcc
	v_cndmask_b32_e32 v119, v119, v135, vcc
	v_cvt_pk_bf16_f32 v136, v112, v113
	v_cvt_pk_bf16_f32 v137, v114, v115
	v_cvt_pk_bf16_f32 v138, v116, v117
	v_cvt_pk_bf16_f32 v139, v118, v119
	v_cndmask_b32_e64 v136, v136, v68, s[18:19]
	v_cndmask_b32_e64 v137, v137, v69, s[18:19]
	v_cndmask_b32_e64 v138, v138, v70, s[18:19]
	v_cndmask_b32_e64 v139, v139, v71, s[18:19]
	global_store_dwordx4 v8, v[136:139], s[12:13]
	s_add_u32 s6, s6, 0x200000
	s_addc_u32 s7, s7, 0
	s_add_u32 s12, s12, 0x80000
	s_addc_u32 s13, s13, 0
	s_waitcnt vmcnt(14)
	v_readlane_b32 s28, v11, 24
	v_readlane_b32 s38, v12, 24
	v_readlane_b32 s29, v11, 25
	v_readlane_b32 s39, v12, 25
	v_readlane_b32 s30, v11, 26
	v_readlane_b32 s40, v12, 26
	v_readlane_b32 s31, v11, 27
	v_readlane_b32 s41, v12, 27
	v_readlane_b32 s34, v11, 28
	v_readlane_b32 s42, v12, 28
	v_readlane_b32 s35, v11, 29
	v_readlane_b32 s43, v12, 29
	v_readlane_b32 s36, v11, 30
	v_readlane_b32 s44, v12, 30
	v_readlane_b32 s37, v11, 31
	v_readlane_b32 s45, v12, 31
	v_mul_f32_e32 v32, s38, v10
	v_mul_f32_e32 v33, s39, v10
	v_mul_f32_e32 v34, s40, v10
	v_mul_f32_e32 v35, s41, v10
	v_mul_f32_e32 v36, s42, v10
	v_mul_f32_e32 v37, s43, v10
	v_mul_f32_e32 v38, s44, v10
	v_mul_f32_e32 v39, s45, v10
	v_lshlrev_b32_e32 v112, 16, v72
	v_and_b32_e32 v113, 0xffff0000, v72
	v_lshlrev_b32_e32 v114, 16, v73
	v_and_b32_e32 v115, 0xffff0000, v73
	v_lshlrev_b32_e32 v116, 16, v74
	v_and_b32_e32 v117, 0xffff0000, v74
	v_lshlrev_b32_e32 v118, 16, v75
	v_and_b32_e32 v119, 0xffff0000, v75
	v_mul_f32_e32 v140, v112, v112
	v_mul_f32_e32 v141, v113, v113
	v_fmac_f32_e32 v140, v114, v114
	v_fmac_f32_e32 v141, v115, v115
	v_fmac_f32_e32 v140, v116, v116
	v_fmac_f32_e32 v141, v117, v117
	v_fmac_f32_e32 v140, v118, v118
	v_fmac_f32_e32 v141, v119, v119
	v_add_f32_e32 v140, v140, v141
	s_nop 1
	v_add_f32_dpp v140, v140, v140 quad_perm:[1,0,3,2] row_mask:0xf bank_mask:0xf bound_ctrl:1
	s_nop 1
	v_add_f32_dpp v140, v140, v140 quad_perm:[2,3,0,1] row_mask:0xf bank_mask:0xf bound_ctrl:1
	s_nop 1
	v_add_f32_dpp v140, v140, v140 row_half_mirror row_mask:0xf bank_mask:0xf bound_ctrl:1
	v_fma_f32 v141, v140, s10, v15
	v_rsq_f32_e32 v141, v141
	s_nop 0
	v_mul_f32_e32 v112, v112, v141
	v_mul_f32_e32 v113, v113, v141
	v_mul_f32_e32 v114, v114, v141
	v_mul_f32_e32 v115, v115, v141
	v_mul_f32_e32 v116, v116, v141
	v_mul_f32_e32 v117, v117, v141
	v_mul_f32_e32 v118, v118, v141
	v_mul_f32_e32 v119, v119, v141
	v_mul_f32_e32 v112, v112, v16
	v_mul_f32_e32 v113, v113, v17
	v_mul_f32_e32 v114, v114, v18
	v_mul_f32_e32 v115, v115, v19
	v_mul_f32_e32 v116, v116, v20
	v_mul_f32_e32 v117, v117, v21
	v_mul_f32_e32 v118, v118, v22
	v_mul_f32_e32 v119, v119, v23
	v_mov_b32_dpp v120, v112 quad_perm:[1,0,3,2] row_mask:0xf bank_mask:0xf
	v_mov_b32_dpp v121, v113 quad_perm:[1,0,3,2] row_mask:0xf bank_mask:0xf
	v_mov_b32_dpp v122, v114 quad_perm:[1,0,3,2] row_mask:0xf bank_mask:0xf
	v_mov_b32_dpp v123, v115 quad_perm:[1,0,3,2] row_mask:0xf bank_mask:0xf
	v_mov_b32_dpp v124, v116 quad_perm:[1,0,3,2] row_mask:0xf bank_mask:0xf
	v_mov_b32_dpp v125, v117 quad_perm:[1,0,3,2] row_mask:0xf bank_mask:0xf
	v_mov_b32_dpp v126, v118 quad_perm:[1,0,3,2] row_mask:0xf bank_mask:0xf
	v_mov_b32_dpp v127, v119 quad_perm:[1,0,3,2] row_mask:0xf bank_mask:0xf
	v_mul_f32_e32 v128, s28, v112
	v_mul_f32_e32 v129, s29, v113
	v_mul_f32_e32 v130, s30, v114
	v_mul_f32_e32 v131, s31, v115
	v_mul_f32_e32 v132, s34, v116
	v_mul_f32_e32 v133, s35, v117
	v_mul_f32_e32 v134, s36, v118
	v_mul_f32_e32 v135, s37, v119
	v_fmac_f32_e32 v128, v32, v120
	v_fmac_f32_e32 v129, v33, v121
	v_fmac_f32_e32 v130, v34, v122
	v_fmac_f32_e32 v131, v35, v123
	v_fmac_f32_e32 v132, v36, v124
	v_fmac_f32_e32 v133, v37, v125
	v_fmac_f32_e32 v134, v38, v126
	v_fmac_f32_e32 v135, v39, v127
	v_cndmask_b32_e32 v112, v112, v128, vcc
	v_cndmask_b32_e32 v113, v113, v129, vcc
	v_cndmask_b32_e32 v114, v114, v130, vcc
	v_cndmask_b32_e32 v115, v115, v131, vcc
	v_cndmask_b32_e32 v116, v116, v132, vcc
	v_cndmask_b32_e32 v117, v117, v133, vcc
	v_cndmask_b32_e32 v118, v118, v134, vcc
	v_cndmask_b32_e32 v119, v119, v135, vcc
	v_mul_f32_e32 v112, 0x3e38aa3b, v112
	v_mul_f32_e32 v113, 0x3e38aa3b, v113
	v_mul_f32_e32 v114, 0x3e38aa3b, v114
	v_mul_f32_e32 v115, 0x3e38aa3b, v115
	v_mul_f32_e32 v116, 0x3e38aa3b, v116
	v_mul_f32_e32 v117, 0x3e38aa3b, v117
	v_mul_f32_e32 v118, 0x3e38aa3b, v118
	v_mul_f32_e32 v119, 0x3e38aa3b, v119
	v_cvt_pk_bf16_f32 v136, v112, v113
	v_cvt_pk_bf16_f32 v137, v114, v115
	v_cvt_pk_bf16_f32 v138, v116, v117
	v_cvt_pk_bf16_f32 v139, v118, v119
	global_store_dwordx4 v7, v[136:139], s[6:7]
	s_nop 1
	v_lshlrev_b32_e32 v112, 16, v76
	v_and_b32_e32 v113, 0xffff0000, v76
	v_lshlrev_b32_e32 v114, 16, v77
	v_and_b32_e32 v115, 0xffff0000, v77
	v_lshlrev_b32_e32 v116, 16, v78
	v_and_b32_e32 v117, 0xffff0000, v78
	v_lshlrev_b32_e32 v118, 16, v79
	v_and_b32_e32 v119, 0xffff0000, v79
	v_mul_f32_e32 v140, v112, v112
	v_mul_f32_e32 v141, v113, v113
	v_fmac_f32_e32 v140, v114, v114
	v_fmac_f32_e32 v141, v115, v115
	v_fmac_f32_e32 v140, v116, v116
	v_fmac_f32_e32 v141, v117, v117
	v_fmac_f32_e32 v140, v118, v118
	v_fmac_f32_e32 v141, v119, v119
	v_add_f32_e32 v140, v140, v141
	s_nop 1
	v_add_f32_dpp v140, v140, v140 quad_perm:[1,0,3,2] row_mask:0xf bank_mask:0xf bound_ctrl:1
	s_nop 1
	v_add_f32_dpp v140, v140, v140 quad_perm:[2,3,0,1] row_mask:0xf bank_mask:0xf bound_ctrl:1
	s_nop 1
	v_add_f32_dpp v140, v140, v140 row_half_mirror row_mask:0xf bank_mask:0xf bound_ctrl:1
	v_fma_f32 v141, v140, s10, v15
	v_rsq_f32_e32 v141, v141
	s_nop 0
	v_mul_f32_e32 v112, v112, v141
	v_mul_f32_e32 v113, v113, v141
	v_mul_f32_e32 v114, v114, v141
	v_mul_f32_e32 v115, v115, v141
	v_mul_f32_e32 v116, v116, v141
	v_mul_f32_e32 v117, v117, v141
	v_mul_f32_e32 v118, v118, v141
	v_mul_f32_e32 v119, v119, v141
	v_mul_f32_e32 v112, v112, v24
	v_mul_f32_e32 v113, v113, v25
	v_mul_f32_e32 v114, v114, v26
	v_mul_f32_e32 v115, v115, v27
	v_mul_f32_e32 v116, v116, v28
	v_mul_f32_e32 v117, v117, v29
	v_mul_f32_e32 v118, v118, v30
	v_mul_f32_e32 v119, v119, v31
	v_mov_b32_dpp v120, v112 quad_perm:[1,0,3,2] row_mask:0xf bank_mask:0xf
	v_mov_b32_dpp v121, v113 quad_perm:[1,0,3,2] row_mask:0xf bank_mask:0xf
	v_mov_b32_dpp v122, v114 quad_perm:[1,0,3,2] row_mask:0xf bank_mask:0xf
	v_mov_b32_dpp v123, v115 quad_perm:[1,0,3,2] row_mask:0xf bank_mask:0xf
	v_mov_b32_dpp v124, v116 quad_perm:[1,0,3,2] row_mask:0xf bank_mask:0xf
	v_mov_b32_dpp v125, v117 quad_perm:[1,0,3,2] row_mask:0xf bank_mask:0xf
	v_mov_b32_dpp v126, v118 quad_perm:[1,0,3,2] row_mask:0xf bank_mask:0xf
	v_mov_b32_dpp v127, v119 quad_perm:[1,0,3,2] row_mask:0xf bank_mask:0xf
	v_mul_f32_e32 v128, s28, v112
	v_mul_f32_e32 v129, s29, v113
	v_mul_f32_e32 v130, s30, v114
	v_mul_f32_e32 v131, s31, v115
	v_mul_f32_e32 v132, s34, v116
	v_mul_f32_e32 v133, s35, v117
	v_mul_f32_e32 v134, s36, v118
	v_mul_f32_e32 v135, s37, v119
	v_fmac_f32_e32 v128, v32, v120
	v_fmac_f32_e32 v129, v33, v121
	v_fmac_f32_e32 v130, v34, v122
	v_fmac_f32_e32 v131, v35, v123
	v_fmac_f32_e32 v132, v36, v124
	v_fmac_f32_e32 v133, v37, v125
	v_fmac_f32_e32 v134, v38, v126
	v_fmac_f32_e32 v135, v39, v127
	v_cndmask_b32_e32 v112, v112, v128, vcc
	v_cndmask_b32_e32 v113, v113, v129, vcc
	v_cndmask_b32_e32 v114, v114, v130, vcc
	v_cndmask_b32_e32 v115, v115, v131, vcc
	v_cndmask_b32_e32 v116, v116, v132, vcc
	v_cndmask_b32_e32 v117, v117, v133, vcc
	v_cndmask_b32_e32 v118, v118, v134, vcc
	v_cndmask_b32_e32 v119, v119, v135, vcc
	v_cvt_pk_bf16_f32 v136, v112, v113
	v_cvt_pk_bf16_f32 v137, v114, v115
	v_cvt_pk_bf16_f32 v138, v116, v117
	v_cvt_pk_bf16_f32 v139, v118, v119
	v_cndmask_b32_e64 v136, v136, v76, s[18:19]
	v_cndmask_b32_e64 v137, v137, v77, s[18:19]
	v_cndmask_b32_e64 v138, v138, v78, s[18:19]
	v_cndmask_b32_e64 v139, v139, v79, s[18:19]
	global_store_dwordx4 v8, v[136:139], s[12:13]
	s_add_u32 s6, s6, 0x200000
	s_addc_u32 s7, s7, 0
	s_add_u32 s12, s12, 0x80000
	s_addc_u32 s13, s13, 0
	s_waitcnt vmcnt(14)
	v_readlane_b32 s28, v11, 32
	v_readlane_b32 s38, v12, 32
	v_readlane_b32 s29, v11, 33
	v_readlane_b32 s39, v12, 33
	v_readlane_b32 s30, v11, 34
	v_readlane_b32 s40, v12, 34
	v_readlane_b32 s31, v11, 35
	v_readlane_b32 s41, v12, 35
	v_readlane_b32 s34, v11, 36
	v_readlane_b32 s42, v12, 36
	v_readlane_b32 s35, v11, 37
	v_readlane_b32 s43, v12, 37
	v_readlane_b32 s36, v11, 38
	v_readlane_b32 s44, v12, 38
	v_readlane_b32 s37, v11, 39
	v_readlane_b32 s45, v12, 39
	v_mul_f32_e32 v32, s38, v10
	v_mul_f32_e32 v33, s39, v10
	v_mul_f32_e32 v34, s40, v10
	v_mul_f32_e32 v35, s41, v10
	v_mul_f32_e32 v36, s42, v10
	v_mul_f32_e32 v37, s43, v10
	v_mul_f32_e32 v38, s44, v10
	v_mul_f32_e32 v39, s45, v10
	v_lshlrev_b32_e32 v112, 16, v80
	v_and_b32_e32 v113, 0xffff0000, v80
	v_lshlrev_b32_e32 v114, 16, v81
	v_and_b32_e32 v115, 0xffff0000, v81
	v_lshlrev_b32_e32 v116, 16, v82
	v_and_b32_e32 v117, 0xffff0000, v82
	v_lshlrev_b32_e32 v118, 16, v83
	v_and_b32_e32 v119, 0xffff0000, v83
	v_mul_f32_e32 v140, v112, v112
	v_mul_f32_e32 v141, v113, v113
	v_fmac_f32_e32 v140, v114, v114
	v_fmac_f32_e32 v141, v115, v115
	v_fmac_f32_e32 v140, v116, v116
	v_fmac_f32_e32 v141, v117, v117
	v_fmac_f32_e32 v140, v118, v118
	v_fmac_f32_e32 v141, v119, v119
	v_add_f32_e32 v140, v140, v141
	s_nop 1
	v_add_f32_dpp v140, v140, v140 quad_perm:[1,0,3,2] row_mask:0xf bank_mask:0xf bound_ctrl:1
	s_nop 1
	v_add_f32_dpp v140, v140, v140 quad_perm:[2,3,0,1] row_mask:0xf bank_mask:0xf bound_ctrl:1
	s_nop 1
	v_add_f32_dpp v140, v140, v140 row_half_mirror row_mask:0xf bank_mask:0xf bound_ctrl:1
	v_fma_f32 v141, v140, s10, v15
	v_rsq_f32_e32 v141, v141
	s_nop 0
	v_mul_f32_e32 v112, v112, v141
	v_mul_f32_e32 v113, v113, v141
	v_mul_f32_e32 v114, v114, v141
	v_mul_f32_e32 v115, v115, v141
	v_mul_f32_e32 v116, v116, v141
	v_mul_f32_e32 v117, v117, v141
	v_mul_f32_e32 v118, v118, v141
	v_mul_f32_e32 v119, v119, v141
	v_mul_f32_e32 v112, v112, v16
	v_mul_f32_e32 v113, v113, v17
	v_mul_f32_e32 v114, v114, v18
	v_mul_f32_e32 v115, v115, v19
	v_mul_f32_e32 v116, v116, v20
	v_mul_f32_e32 v117, v117, v21
	v_mul_f32_e32 v118, v118, v22
	v_mul_f32_e32 v119, v119, v23
	v_mov_b32_dpp v120, v112 quad_perm:[1,0,3,2] row_mask:0xf bank_mask:0xf
	v_mov_b32_dpp v121, v113 quad_perm:[1,0,3,2] row_mask:0xf bank_mask:0xf
	v_mov_b32_dpp v122, v114 quad_perm:[1,0,3,2] row_mask:0xf bank_mask:0xf
	v_mov_b32_dpp v123, v115 quad_perm:[1,0,3,2] row_mask:0xf bank_mask:0xf
	v_mov_b32_dpp v124, v116 quad_perm:[1,0,3,2] row_mask:0xf bank_mask:0xf
	v_mov_b32_dpp v125, v117 quad_perm:[1,0,3,2] row_mask:0xf bank_mask:0xf
	v_mov_b32_dpp v126, v118 quad_perm:[1,0,3,2] row_mask:0xf bank_mask:0xf
	v_mov_b32_dpp v127, v119 quad_perm:[1,0,3,2] row_mask:0xf bank_mask:0xf
	v_mul_f32_e32 v128, s28, v112
	v_mul_f32_e32 v129, s29, v113
	v_mul_f32_e32 v130, s30, v114
	v_mul_f32_e32 v131, s31, v115
	v_mul_f32_e32 v132, s34, v116
	v_mul_f32_e32 v133, s35, v117
	v_mul_f32_e32 v134, s36, v118
	v_mul_f32_e32 v135, s37, v119
	v_fmac_f32_e32 v128, v32, v120
	v_fmac_f32_e32 v129, v33, v121
	v_fmac_f32_e32 v130, v34, v122
	v_fmac_f32_e32 v131, v35, v123
	v_fmac_f32_e32 v132, v36, v124
	v_fmac_f32_e32 v133, v37, v125
	v_fmac_f32_e32 v134, v38, v126
	v_fmac_f32_e32 v135, v39, v127
	v_cndmask_b32_e32 v112, v112, v128, vcc
	v_cndmask_b32_e32 v113, v113, v129, vcc
	v_cndmask_b32_e32 v114, v114, v130, vcc
	v_cndmask_b32_e32 v115, v115, v131, vcc
	v_cndmask_b32_e32 v116, v116, v132, vcc
	v_cndmask_b32_e32 v117, v117, v133, vcc
	v_cndmask_b32_e32 v118, v118, v134, vcc
	v_cndmask_b32_e32 v119, v119, v135, vcc
	v_mul_f32_e32 v112, 0x3e38aa3b, v112
	v_mul_f32_e32 v113, 0x3e38aa3b, v113
	v_mul_f32_e32 v114, 0x3e38aa3b, v114
	v_mul_f32_e32 v115, 0x3e38aa3b, v115
	v_mul_f32_e32 v116, 0x3e38aa3b, v116
	v_mul_f32_e32 v117, 0x3e38aa3b, v117
	v_mul_f32_e32 v118, 0x3e38aa3b, v118
	v_mul_f32_e32 v119, 0x3e38aa3b, v119
	v_cvt_pk_bf16_f32 v136, v112, v113
	v_cvt_pk_bf16_f32 v137, v114, v115
	v_cvt_pk_bf16_f32 v138, v116, v117
	v_cvt_pk_bf16_f32 v139, v118, v119
	global_store_dwordx4 v7, v[136:139], s[6:7]
	s_nop 1
	v_lshlrev_b32_e32 v112, 16, v84
	v_and_b32_e32 v113, 0xffff0000, v84
	v_lshlrev_b32_e32 v114, 16, v85
	v_and_b32_e32 v115, 0xffff0000, v85
	v_lshlrev_b32_e32 v116, 16, v86
	v_and_b32_e32 v117, 0xffff0000, v86
	v_lshlrev_b32_e32 v118, 16, v87
	v_and_b32_e32 v119, 0xffff0000, v87
	v_mul_f32_e32 v140, v112, v112
	v_mul_f32_e32 v141, v113, v113
	v_fmac_f32_e32 v140, v114, v114
	v_fmac_f32_e32 v141, v115, v115
	v_fmac_f32_e32 v140, v116, v116
	v_fmac_f32_e32 v141, v117, v117
	v_fmac_f32_e32 v140, v118, v118
	v_fmac_f32_e32 v141, v119, v119
	v_add_f32_e32 v140, v140, v141
	s_nop 1
	v_add_f32_dpp v140, v140, v140 quad_perm:[1,0,3,2] row_mask:0xf bank_mask:0xf bound_ctrl:1
	s_nop 1
	v_add_f32_dpp v140, v140, v140 quad_perm:[2,3,0,1] row_mask:0xf bank_mask:0xf bound_ctrl:1
	s_nop 1
	v_add_f32_dpp v140, v140, v140 row_half_mirror row_mask:0xf bank_mask:0xf bound_ctrl:1
	v_fma_f32 v141, v140, s10, v15
	v_rsq_f32_e32 v141, v141
	s_nop 0
	v_mul_f32_e32 v112, v112, v141
	v_mul_f32_e32 v113, v113, v141
	v_mul_f32_e32 v114, v114, v141
	v_mul_f32_e32 v115, v115, v141
	v_mul_f32_e32 v116, v116, v141
	v_mul_f32_e32 v117, v117, v141
	v_mul_f32_e32 v118, v118, v141
	v_mul_f32_e32 v119, v119, v141
	v_mul_f32_e32 v112, v112, v24
	v_mul_f32_e32 v113, v113, v25
	v_mul_f32_e32 v114, v114, v26
	v_mul_f32_e32 v115, v115, v27
	v_mul_f32_e32 v116, v116, v28
	v_mul_f32_e32 v117, v117, v29
	v_mul_f32_e32 v118, v118, v30
	v_mul_f32_e32 v119, v119, v31
	v_mov_b32_dpp v120, v112 quad_perm:[1,0,3,2] row_mask:0xf bank_mask:0xf
	v_mov_b32_dpp v121, v113 quad_perm:[1,0,3,2] row_mask:0xf bank_mask:0xf
	v_mov_b32_dpp v122, v114 quad_perm:[1,0,3,2] row_mask:0xf bank_mask:0xf
	v_mov_b32_dpp v123, v115 quad_perm:[1,0,3,2] row_mask:0xf bank_mask:0xf
	v_mov_b32_dpp v124, v116 quad_perm:[1,0,3,2] row_mask:0xf bank_mask:0xf
	v_mov_b32_dpp v125, v117 quad_perm:[1,0,3,2] row_mask:0xf bank_mask:0xf
	v_mov_b32_dpp v126, v118 quad_perm:[1,0,3,2] row_mask:0xf bank_mask:0xf
	v_mov_b32_dpp v127, v119 quad_perm:[1,0,3,2] row_mask:0xf bank_mask:0xf
	v_mul_f32_e32 v128, s28, v112
	v_mul_f32_e32 v129, s29, v113
	v_mul_f32_e32 v130, s30, v114
	v_mul_f32_e32 v131, s31, v115
	v_mul_f32_e32 v132, s34, v116
	v_mul_f32_e32 v133, s35, v117
	v_mul_f32_e32 v134, s36, v118
	v_mul_f32_e32 v135, s37, v119
	v_fmac_f32_e32 v128, v32, v120
	v_fmac_f32_e32 v129, v33, v121
	v_fmac_f32_e32 v130, v34, v122
	v_fmac_f32_e32 v131, v35, v123
	v_fmac_f32_e32 v132, v36, v124
	v_fmac_f32_e32 v133, v37, v125
	v_fmac_f32_e32 v134, v38, v126
	v_fmac_f32_e32 v135, v39, v127
	v_cndmask_b32_e32 v112, v112, v128, vcc
	v_cndmask_b32_e32 v113, v113, v129, vcc
	v_cndmask_b32_e32 v114, v114, v130, vcc
	v_cndmask_b32_e32 v115, v115, v131, vcc
	v_cndmask_b32_e32 v116, v116, v132, vcc
	v_cndmask_b32_e32 v117, v117, v133, vcc
	v_cndmask_b32_e32 v118, v118, v134, vcc
	v_cndmask_b32_e32 v119, v119, v135, vcc
	v_cvt_pk_bf16_f32 v136, v112, v113
	v_cvt_pk_bf16_f32 v137, v114, v115
	v_cvt_pk_bf16_f32 v138, v116, v117
	v_cvt_pk_bf16_f32 v139, v118, v119
	v_cndmask_b32_e64 v136, v136, v84, s[18:19]
	v_cndmask_b32_e64 v137, v137, v85, s[18:19]
	v_cndmask_b32_e64 v138, v138, v86, s[18:19]
	v_cndmask_b32_e64 v139, v139, v87, s[18:19]
	global_store_dwordx4 v8, v[136:139], s[12:13]
	s_add_u32 s6, s6, 0x200000
	s_addc_u32 s7, s7, 0
	s_add_u32 s12, s12, 0x80000
	s_addc_u32 s13, s13, 0
	s_waitcnt vmcnt(14)
	v_readlane_b32 s28, v11, 40
	v_readlane_b32 s38, v12, 40
	v_readlane_b32 s29, v11, 41
	v_readlane_b32 s39, v12, 41
	v_readlane_b32 s30, v11, 42
	v_readlane_b32 s40, v12, 42
	v_readlane_b32 s31, v11, 43
	v_readlane_b32 s41, v12, 43
	v_readlane_b32 s34, v11, 44
	v_readlane_b32 s42, v12, 44
	v_readlane_b32 s35, v11, 45
	v_readlane_b32 s43, v12, 45
	v_readlane_b32 s36, v11, 46
	v_readlane_b32 s44, v12, 46
	v_readlane_b32 s37, v11, 47
	v_readlane_b32 s45, v12, 47
	v_mul_f32_e32 v32, s38, v10
	v_mul_f32_e32 v33, s39, v10
	v_mul_f32_e32 v34, s40, v10
	v_mul_f32_e32 v35, s41, v10
	v_mul_f32_e32 v36, s42, v10
	v_mul_f32_e32 v37, s43, v10
	v_mul_f32_e32 v38, s44, v10
	v_mul_f32_e32 v39, s45, v10
	v_lshlrev_b32_e32 v112, 16, v88
	v_and_b32_e32 v113, 0xffff0000, v88
	v_lshlrev_b32_e32 v114, 16, v89
	v_and_b32_e32 v115, 0xffff0000, v89
	v_lshlrev_b32_e32 v116, 16, v90
	v_and_b32_e32 v117, 0xffff0000, v90
	v_lshlrev_b32_e32 v118, 16, v91
	v_and_b32_e32 v119, 0xffff0000, v91
	v_mul_f32_e32 v140, v112, v112
	v_mul_f32_e32 v141, v113, v113
	v_fmac_f32_e32 v140, v114, v114
	v_fmac_f32_e32 v141, v115, v115
	v_fmac_f32_e32 v140, v116, v116
	v_fmac_f32_e32 v141, v117, v117
	v_fmac_f32_e32 v140, v118, v118
	v_fmac_f32_e32 v141, v119, v119
	v_add_f32_e32 v140, v140, v141
	s_nop 1
	v_add_f32_dpp v140, v140, v140 quad_perm:[1,0,3,2] row_mask:0xf bank_mask:0xf bound_ctrl:1
	s_nop 1
	v_add_f32_dpp v140, v140, v140 quad_perm:[2,3,0,1] row_mask:0xf bank_mask:0xf bound_ctrl:1
	s_nop 1
	v_add_f32_dpp v140, v140, v140 row_half_mirror row_mask:0xf bank_mask:0xf bound_ctrl:1
	v_fma_f32 v141, v140, s10, v15
	v_rsq_f32_e32 v141, v141
	s_nop 0
	v_mul_f32_e32 v112, v112, v141
	v_mul_f32_e32 v113, v113, v141
	v_mul_f32_e32 v114, v114, v141
	v_mul_f32_e32 v115, v115, v141
	v_mul_f32_e32 v116, v116, v141
	v_mul_f32_e32 v117, v117, v141
	v_mul_f32_e32 v118, v118, v141
	v_mul_f32_e32 v119, v119, v141
	v_mul_f32_e32 v112, v112, v16
	v_mul_f32_e32 v113, v113, v17
	v_mul_f32_e32 v114, v114, v18
	v_mul_f32_e32 v115, v115, v19
	v_mul_f32_e32 v116, v116, v20
	v_mul_f32_e32 v117, v117, v21
	v_mul_f32_e32 v118, v118, v22
	v_mul_f32_e32 v119, v119, v23
	v_mov_b32_dpp v120, v112 quad_perm:[1,0,3,2] row_mask:0xf bank_mask:0xf
	v_mov_b32_dpp v121, v113 quad_perm:[1,0,3,2] row_mask:0xf bank_mask:0xf
	v_mov_b32_dpp v122, v114 quad_perm:[1,0,3,2] row_mask:0xf bank_mask:0xf
	v_mov_b32_dpp v123, v115 quad_perm:[1,0,3,2] row_mask:0xf bank_mask:0xf
	v_mov_b32_dpp v124, v116 quad_perm:[1,0,3,2] row_mask:0xf bank_mask:0xf
	v_mov_b32_dpp v125, v117 quad_perm:[1,0,3,2] row_mask:0xf bank_mask:0xf
	v_mov_b32_dpp v126, v118 quad_perm:[1,0,3,2] row_mask:0xf bank_mask:0xf
	v_mov_b32_dpp v127, v119 quad_perm:[1,0,3,2] row_mask:0xf bank_mask:0xf
	v_mul_f32_e32 v128, s28, v112
	v_mul_f32_e32 v129, s29, v113
	v_mul_f32_e32 v130, s30, v114
	v_mul_f32_e32 v131, s31, v115
	v_mul_f32_e32 v132, s34, v116
	v_mul_f32_e32 v133, s35, v117
	v_mul_f32_e32 v134, s36, v118
	v_mul_f32_e32 v135, s37, v119
	v_fmac_f32_e32 v128, v32, v120
	v_fmac_f32_e32 v129, v33, v121
	v_fmac_f32_e32 v130, v34, v122
	v_fmac_f32_e32 v131, v35, v123
	v_fmac_f32_e32 v132, v36, v124
	v_fmac_f32_e32 v133, v37, v125
	v_fmac_f32_e32 v134, v38, v126
	v_fmac_f32_e32 v135, v39, v127
	v_cndmask_b32_e32 v112, v112, v128, vcc
	v_cndmask_b32_e32 v113, v113, v129, vcc
	v_cndmask_b32_e32 v114, v114, v130, vcc
	v_cndmask_b32_e32 v115, v115, v131, vcc
	v_cndmask_b32_e32 v116, v116, v132, vcc
	v_cndmask_b32_e32 v117, v117, v133, vcc
	v_cndmask_b32_e32 v118, v118, v134, vcc
	v_cndmask_b32_e32 v119, v119, v135, vcc
	v_mul_f32_e32 v112, 0x3e38aa3b, v112
	v_mul_f32_e32 v113, 0x3e38aa3b, v113
	v_mul_f32_e32 v114, 0x3e38aa3b, v114
	v_mul_f32_e32 v115, 0x3e38aa3b, v115
	v_mul_f32_e32 v116, 0x3e38aa3b, v116
	v_mul_f32_e32 v117, 0x3e38aa3b, v117
	v_mul_f32_e32 v118, 0x3e38aa3b, v118
	v_mul_f32_e32 v119, 0x3e38aa3b, v119
	v_cvt_pk_bf16_f32 v136, v112, v113
	v_cvt_pk_bf16_f32 v137, v114, v115
	v_cvt_pk_bf16_f32 v138, v116, v117
	v_cvt_pk_bf16_f32 v139, v118, v119
	global_store_dwordx4 v7, v[136:139], s[6:7]
	s_nop 1
	v_lshlrev_b32_e32 v112, 16, v92
	v_and_b32_e32 v113, 0xffff0000, v92
	v_lshlrev_b32_e32 v114, 16, v93
	v_and_b32_e32 v115, 0xffff0000, v93
	v_lshlrev_b32_e32 v116, 16, v94
	v_and_b32_e32 v117, 0xffff0000, v94
	v_lshlrev_b32_e32 v118, 16, v95
	v_and_b32_e32 v119, 0xffff0000, v95
	v_mul_f32_e32 v140, v112, v112
	v_mul_f32_e32 v141, v113, v113
	v_fmac_f32_e32 v140, v114, v114
	v_fmac_f32_e32 v141, v115, v115
	v_fmac_f32_e32 v140, v116, v116
	v_fmac_f32_e32 v141, v117, v117
	v_fmac_f32_e32 v140, v118, v118
	v_fmac_f32_e32 v141, v119, v119
	v_add_f32_e32 v140, v140, v141
	s_nop 1
	v_add_f32_dpp v140, v140, v140 quad_perm:[1,0,3,2] row_mask:0xf bank_mask:0xf bound_ctrl:1
	s_nop 1
	v_add_f32_dpp v140, v140, v140 quad_perm:[2,3,0,1] row_mask:0xf bank_mask:0xf bound_ctrl:1
	s_nop 1
	v_add_f32_dpp v140, v140, v140 row_half_mirror row_mask:0xf bank_mask:0xf bound_ctrl:1
	v_fma_f32 v141, v140, s10, v15
	v_rsq_f32_e32 v141, v141
	s_nop 0
	v_mul_f32_e32 v112, v112, v141
	v_mul_f32_e32 v113, v113, v141
	v_mul_f32_e32 v114, v114, v141
	v_mul_f32_e32 v115, v115, v141
	v_mul_f32_e32 v116, v116, v141
	v_mul_f32_e32 v117, v117, v141
	v_mul_f32_e32 v118, v118, v141
	v_mul_f32_e32 v119, v119, v141
	v_mul_f32_e32 v112, v112, v24
	v_mul_f32_e32 v113, v113, v25
	v_mul_f32_e32 v114, v114, v26
	v_mul_f32_e32 v115, v115, v27
	v_mul_f32_e32 v116, v116, v28
	v_mul_f32_e32 v117, v117, v29
	v_mul_f32_e32 v118, v118, v30
	v_mul_f32_e32 v119, v119, v31
	v_mov_b32_dpp v120, v112 quad_perm:[1,0,3,2] row_mask:0xf bank_mask:0xf
	v_mov_b32_dpp v121, v113 quad_perm:[1,0,3,2] row_mask:0xf bank_mask:0xf
	v_mov_b32_dpp v122, v114 quad_perm:[1,0,3,2] row_mask:0xf bank_mask:0xf
	v_mov_b32_dpp v123, v115 quad_perm:[1,0,3,2] row_mask:0xf bank_mask:0xf
	v_mov_b32_dpp v124, v116 quad_perm:[1,0,3,2] row_mask:0xf bank_mask:0xf
	v_mov_b32_dpp v125, v117 quad_perm:[1,0,3,2] row_mask:0xf bank_mask:0xf
	v_mov_b32_dpp v126, v118 quad_perm:[1,0,3,2] row_mask:0xf bank_mask:0xf
	v_mov_b32_dpp v127, v119 quad_perm:[1,0,3,2] row_mask:0xf bank_mask:0xf
	v_mul_f32_e32 v128, s28, v112
	v_mul_f32_e32 v129, s29, v113
	v_mul_f32_e32 v130, s30, v114
	v_mul_f32_e32 v131, s31, v115
	v_mul_f32_e32 v132, s34, v116
	v_mul_f32_e32 v133, s35, v117
	v_mul_f32_e32 v134, s36, v118
	v_mul_f32_e32 v135, s37, v119
	v_fmac_f32_e32 v128, v32, v120
	v_fmac_f32_e32 v129, v33, v121
	v_fmac_f32_e32 v130, v34, v122
	v_fmac_f32_e32 v131, v35, v123
	v_fmac_f32_e32 v132, v36, v124
	v_fmac_f32_e32 v133, v37, v125
	v_fmac_f32_e32 v134, v38, v126
	v_fmac_f32_e32 v135, v39, v127
	v_cndmask_b32_e32 v112, v112, v128, vcc
	v_cndmask_b32_e32 v113, v113, v129, vcc
	v_cndmask_b32_e32 v114, v114, v130, vcc
	v_cndmask_b32_e32 v115, v115, v131, vcc
	v_cndmask_b32_e32 v116, v116, v132, vcc
	v_cndmask_b32_e32 v117, v117, v133, vcc
	v_cndmask_b32_e32 v118, v118, v134, vcc
	v_cndmask_b32_e32 v119, v119, v135, vcc
	v_cvt_pk_bf16_f32 v136, v112, v113
	v_cvt_pk_bf16_f32 v137, v114, v115
	v_cvt_pk_bf16_f32 v138, v116, v117
	v_cvt_pk_bf16_f32 v139, v118, v119
	v_cndmask_b32_e64 v136, v136, v92, s[18:19]
	v_cndmask_b32_e64 v137, v137, v93, s[18:19]
	v_cndmask_b32_e64 v138, v138, v94, s[18:19]
	v_cndmask_b32_e64 v139, v139, v95, s[18:19]
	global_store_dwordx4 v8, v[136:139], s[12:13]
	s_add_u32 s6, s6, 0x200000
	s_addc_u32 s7, s7, 0
	s_add_u32 s12, s12, 0x80000
	s_addc_u32 s13, s13, 0
	s_waitcnt vmcnt(14)
	v_readlane_b32 s28, v11, 48
	v_readlane_b32 s38, v12, 48
	v_readlane_b32 s29, v11, 49
	v_readlane_b32 s39, v12, 49
	v_readlane_b32 s30, v11, 50
	v_readlane_b32 s40, v12, 50
	v_readlane_b32 s31, v11, 51
	v_readlane_b32 s41, v12, 51
	v_readlane_b32 s34, v11, 52
	v_readlane_b32 s42, v12, 52
	v_readlane_b32 s35, v11, 53
	v_readlane_b32 s43, v12, 53
	v_readlane_b32 s36, v11, 54
	v_readlane_b32 s44, v12, 54
	v_readlane_b32 s37, v11, 55
	v_readlane_b32 s45, v12, 55
	v_mul_f32_e32 v32, s38, v10
	v_mul_f32_e32 v33, s39, v10
	v_mul_f32_e32 v34, s40, v10
	v_mul_f32_e32 v35, s41, v10
	v_mul_f32_e32 v36, s42, v10
	v_mul_f32_e32 v37, s43, v10
	v_mul_f32_e32 v38, s44, v10
	v_mul_f32_e32 v39, s45, v10
	v_lshlrev_b32_e32 v112, 16, v96
	v_and_b32_e32 v113, 0xffff0000, v96
	v_lshlrev_b32_e32 v114, 16, v97
	v_and_b32_e32 v115, 0xffff0000, v97
	v_lshlrev_b32_e32 v116, 16, v98
	v_and_b32_e32 v117, 0xffff0000, v98
	v_lshlrev_b32_e32 v118, 16, v99
	v_and_b32_e32 v119, 0xffff0000, v99
	v_mul_f32_e32 v140, v112, v112
	v_mul_f32_e32 v141, v113, v113
	v_fmac_f32_e32 v140, v114, v114
	v_fmac_f32_e32 v141, v115, v115
	v_fmac_f32_e32 v140, v116, v116
	v_fmac_f32_e32 v141, v117, v117
	v_fmac_f32_e32 v140, v118, v118
	v_fmac_f32_e32 v141, v119, v119
	v_add_f32_e32 v140, v140, v141
	s_nop 1
	v_add_f32_dpp v140, v140, v140 quad_perm:[1,0,3,2] row_mask:0xf bank_mask:0xf bound_ctrl:1
	s_nop 1
	v_add_f32_dpp v140, v140, v140 quad_perm:[2,3,0,1] row_mask:0xf bank_mask:0xf bound_ctrl:1
	s_nop 1
	v_add_f32_dpp v140, v140, v140 row_half_mirror row_mask:0xf bank_mask:0xf bound_ctrl:1
	v_fma_f32 v141, v140, s10, v15
	v_rsq_f32_e32 v141, v141
	s_nop 0
	v_mul_f32_e32 v112, v112, v141
	v_mul_f32_e32 v113, v113, v141
	v_mul_f32_e32 v114, v114, v141
	v_mul_f32_e32 v115, v115, v141
	v_mul_f32_e32 v116, v116, v141
	v_mul_f32_e32 v117, v117, v141
	v_mul_f32_e32 v118, v118, v141
	v_mul_f32_e32 v119, v119, v141
	v_mul_f32_e32 v112, v112, v16
	v_mul_f32_e32 v113, v113, v17
	v_mul_f32_e32 v114, v114, v18
	v_mul_f32_e32 v115, v115, v19
	v_mul_f32_e32 v116, v116, v20
	v_mul_f32_e32 v117, v117, v21
	v_mul_f32_e32 v118, v118, v22
	v_mul_f32_e32 v119, v119, v23
	v_mov_b32_dpp v120, v112 quad_perm:[1,0,3,2] row_mask:0xf bank_mask:0xf
	v_mov_b32_dpp v121, v113 quad_perm:[1,0,3,2] row_mask:0xf bank_mask:0xf
	v_mov_b32_dpp v122, v114 quad_perm:[1,0,3,2] row_mask:0xf bank_mask:0xf
	v_mov_b32_dpp v123, v115 quad_perm:[1,0,3,2] row_mask:0xf bank_mask:0xf
	v_mov_b32_dpp v124, v116 quad_perm:[1,0,3,2] row_mask:0xf bank_mask:0xf
	v_mov_b32_dpp v125, v117 quad_perm:[1,0,3,2] row_mask:0xf bank_mask:0xf
	v_mov_b32_dpp v126, v118 quad_perm:[1,0,3,2] row_mask:0xf bank_mask:0xf
	v_mov_b32_dpp v127, v119 quad_perm:[1,0,3,2] row_mask:0xf bank_mask:0xf
	v_mul_f32_e32 v128, s28, v112
	v_mul_f32_e32 v129, s29, v113
	v_mul_f32_e32 v130, s30, v114
	v_mul_f32_e32 v131, s31, v115
	v_mul_f32_e32 v132, s34, v116
	v_mul_f32_e32 v133, s35, v117
	v_mul_f32_e32 v134, s36, v118
	v_mul_f32_e32 v135, s37, v119
	v_fmac_f32_e32 v128, v32, v120
	v_fmac_f32_e32 v129, v33, v121
	v_fmac_f32_e32 v130, v34, v122
	v_fmac_f32_e32 v131, v35, v123
	v_fmac_f32_e32 v132, v36, v124
	v_fmac_f32_e32 v133, v37, v125
	v_fmac_f32_e32 v134, v38, v126
	v_fmac_f32_e32 v135, v39, v127
	v_cndmask_b32_e32 v112, v112, v128, vcc
	v_cndmask_b32_e32 v113, v113, v129, vcc
	v_cndmask_b32_e32 v114, v114, v130, vcc
	v_cndmask_b32_e32 v115, v115, v131, vcc
	v_cndmask_b32_e32 v116, v116, v132, vcc
	v_cndmask_b32_e32 v117, v117, v133, vcc
	v_cndmask_b32_e32 v118, v118, v134, vcc
	v_cndmask_b32_e32 v119, v119, v135, vcc
	v_mul_f32_e32 v112, 0x3e38aa3b, v112
	v_mul_f32_e32 v113, 0x3e38aa3b, v113
	v_mul_f32_e32 v114, 0x3e38aa3b, v114
	v_mul_f32_e32 v115, 0x3e38aa3b, v115
	v_mul_f32_e32 v116, 0x3e38aa3b, v116
	v_mul_f32_e32 v117, 0x3e38aa3b, v117
	v_mul_f32_e32 v118, 0x3e38aa3b, v118
	v_mul_f32_e32 v119, 0x3e38aa3b, v119
	v_cvt_pk_bf16_f32 v136, v112, v113
	v_cvt_pk_bf16_f32 v137, v114, v115
	v_cvt_pk_bf16_f32 v138, v116, v117
	v_cvt_pk_bf16_f32 v139, v118, v119
	global_store_dwordx4 v7, v[136:139], s[6:7]
	s_nop 1
	v_lshlrev_b32_e32 v112, 16, v100
	v_and_b32_e32 v113, 0xffff0000, v100
	v_lshlrev_b32_e32 v114, 16, v101
	v_and_b32_e32 v115, 0xffff0000, v101
	v_lshlrev_b32_e32 v116, 16, v102
	v_and_b32_e32 v117, 0xffff0000, v102
	v_lshlrev_b32_e32 v118, 16, v103
	v_and_b32_e32 v119, 0xffff0000, v103
	v_mul_f32_e32 v140, v112, v112
	v_mul_f32_e32 v141, v113, v113
	v_fmac_f32_e32 v140, v114, v114
	v_fmac_f32_e32 v141, v115, v115
	v_fmac_f32_e32 v140, v116, v116
	v_fmac_f32_e32 v141, v117, v117
	v_fmac_f32_e32 v140, v118, v118
	v_fmac_f32_e32 v141, v119, v119
	v_add_f32_e32 v140, v140, v141
	s_nop 1
	v_add_f32_dpp v140, v140, v140 quad_perm:[1,0,3,2] row_mask:0xf bank_mask:0xf bound_ctrl:1
	s_nop 1
	v_add_f32_dpp v140, v140, v140 quad_perm:[2,3,0,1] row_mask:0xf bank_mask:0xf bound_ctrl:1
	s_nop 1
	v_add_f32_dpp v140, v140, v140 row_half_mirror row_mask:0xf bank_mask:0xf bound_ctrl:1
	v_fma_f32 v141, v140, s10, v15
	v_rsq_f32_e32 v141, v141
	s_nop 0
	v_mul_f32_e32 v112, v112, v141
	v_mul_f32_e32 v113, v113, v141
	v_mul_f32_e32 v114, v114, v141
	v_mul_f32_e32 v115, v115, v141
	v_mul_f32_e32 v116, v116, v141
	v_mul_f32_e32 v117, v117, v141
	v_mul_f32_e32 v118, v118, v141
	v_mul_f32_e32 v119, v119, v141
	v_mul_f32_e32 v112, v112, v24
	v_mul_f32_e32 v113, v113, v25
	v_mul_f32_e32 v114, v114, v26
	v_mul_f32_e32 v115, v115, v27
	v_mul_f32_e32 v116, v116, v28
	v_mul_f32_e32 v117, v117, v29
	v_mul_f32_e32 v118, v118, v30
	v_mul_f32_e32 v119, v119, v31
	v_mov_b32_dpp v120, v112 quad_perm:[1,0,3,2] row_mask:0xf bank_mask:0xf
	v_mov_b32_dpp v121, v113 quad_perm:[1,0,3,2] row_mask:0xf bank_mask:0xf
	v_mov_b32_dpp v122, v114 quad_perm:[1,0,3,2] row_mask:0xf bank_mask:0xf
	v_mov_b32_dpp v123, v115 quad_perm:[1,0,3,2] row_mask:0xf bank_mask:0xf
	v_mov_b32_dpp v124, v116 quad_perm:[1,0,3,2] row_mask:0xf bank_mask:0xf
	v_mov_b32_dpp v125, v117 quad_perm:[1,0,3,2] row_mask:0xf bank_mask:0xf
	v_mov_b32_dpp v126, v118 quad_perm:[1,0,3,2] row_mask:0xf bank_mask:0xf
	v_mov_b32_dpp v127, v119 quad_perm:[1,0,3,2] row_mask:0xf bank_mask:0xf
	v_mul_f32_e32 v128, s28, v112
	v_mul_f32_e32 v129, s29, v113
	v_mul_f32_e32 v130, s30, v114
	v_mul_f32_e32 v131, s31, v115
	v_mul_f32_e32 v132, s34, v116
	v_mul_f32_e32 v133, s35, v117
	v_mul_f32_e32 v134, s36, v118
	v_mul_f32_e32 v135, s37, v119
	v_fmac_f32_e32 v128, v32, v120
	v_fmac_f32_e32 v129, v33, v121
	v_fmac_f32_e32 v130, v34, v122
	v_fmac_f32_e32 v131, v35, v123
	v_fmac_f32_e32 v132, v36, v124
	v_fmac_f32_e32 v133, v37, v125
	v_fmac_f32_e32 v134, v38, v126
	v_fmac_f32_e32 v135, v39, v127
	v_cndmask_b32_e32 v112, v112, v128, vcc
	v_cndmask_b32_e32 v113, v113, v129, vcc
	v_cndmask_b32_e32 v114, v114, v130, vcc
	v_cndmask_b32_e32 v115, v115, v131, vcc
	v_cndmask_b32_e32 v116, v116, v132, vcc
	v_cndmask_b32_e32 v117, v117, v133, vcc
	v_cndmask_b32_e32 v118, v118, v134, vcc
	v_cndmask_b32_e32 v119, v119, v135, vcc
	v_cvt_pk_bf16_f32 v136, v112, v113
	v_cvt_pk_bf16_f32 v137, v114, v115
	v_cvt_pk_bf16_f32 v138, v116, v117
	v_cvt_pk_bf16_f32 v139, v118, v119
	v_cndmask_b32_e64 v136, v136, v100, s[18:19]
	v_cndmask_b32_e64 v137, v137, v101, s[18:19]
	v_cndmask_b32_e64 v138, v138, v102, s[18:19]
	v_cndmask_b32_e64 v139, v139, v103, s[18:19]
	global_store_dwordx4 v8, v[136:139], s[12:13]
	s_add_u32 s6, s6, 0x200000
	s_addc_u32 s7, s7, 0
	s_add_u32 s12, s12, 0x80000
	s_addc_u32 s13, s13, 0
	s_waitcnt vmcnt(14)
	v_readlane_b32 s28, v11, 56
	v_readlane_b32 s38, v12, 56
	v_readlane_b32 s29, v11, 57
	v_readlane_b32 s39, v12, 57
	v_readlane_b32 s30, v11, 58
	v_readlane_b32 s40, v12, 58
	v_readlane_b32 s31, v11, 59
	v_readlane_b32 s41, v12, 59
	v_readlane_b32 s34, v11, 60
	v_readlane_b32 s42, v12, 60
	v_readlane_b32 s35, v11, 61
	v_readlane_b32 s43, v12, 61
	v_readlane_b32 s36, v11, 62
	v_readlane_b32 s44, v12, 62
	v_readlane_b32 s37, v11, 63
	v_readlane_b32 s45, v12, 63
	v_mul_f32_e32 v32, s38, v10
	v_mul_f32_e32 v33, s39, v10
	v_mul_f32_e32 v34, s40, v10
	v_mul_f32_e32 v35, s41, v10
	v_mul_f32_e32 v36, s42, v10
	v_mul_f32_e32 v37, s43, v10
	v_mul_f32_e32 v38, s44, v10
	v_mul_f32_e32 v39, s45, v10
	v_lshlrev_b32_e32 v112, 16, v104
	v_and_b32_e32 v113, 0xffff0000, v104
	v_lshlrev_b32_e32 v114, 16, v105
	v_and_b32_e32 v115, 0xffff0000, v105
	v_lshlrev_b32_e32 v116, 16, v106
	v_and_b32_e32 v117, 0xffff0000, v106
	v_lshlrev_b32_e32 v118, 16, v107
	v_and_b32_e32 v119, 0xffff0000, v107
	v_mul_f32_e32 v140, v112, v112
	v_mul_f32_e32 v141, v113, v113
	v_fmac_f32_e32 v140, v114, v114
	v_fmac_f32_e32 v141, v115, v115
	v_fmac_f32_e32 v140, v116, v116
	v_fmac_f32_e32 v141, v117, v117
	v_fmac_f32_e32 v140, v118, v118
	v_fmac_f32_e32 v141, v119, v119
	v_add_f32_e32 v140, v140, v141
	s_nop 1
	v_add_f32_dpp v140, v140, v140 quad_perm:[1,0,3,2] row_mask:0xf bank_mask:0xf bound_ctrl:1
	s_nop 1
	v_add_f32_dpp v140, v140, v140 quad_perm:[2,3,0,1] row_mask:0xf bank_mask:0xf bound_ctrl:1
	s_nop 1
	v_add_f32_dpp v140, v140, v140 row_half_mirror row_mask:0xf bank_mask:0xf bound_ctrl:1
	v_fma_f32 v141, v140, s10, v15
	v_rsq_f32_e32 v141, v141
	s_nop 0
	v_mul_f32_e32 v112, v112, v141
	v_mul_f32_e32 v113, v113, v141
	v_mul_f32_e32 v114, v114, v141
	v_mul_f32_e32 v115, v115, v141
	v_mul_f32_e32 v116, v116, v141
	v_mul_f32_e32 v117, v117, v141
	v_mul_f32_e32 v118, v118, v141
	v_mul_f32_e32 v119, v119, v141
	v_mul_f32_e32 v112, v112, v16
	v_mul_f32_e32 v113, v113, v17
	v_mul_f32_e32 v114, v114, v18
	v_mul_f32_e32 v115, v115, v19
	v_mul_f32_e32 v116, v116, v20
	v_mul_f32_e32 v117, v117, v21
	v_mul_f32_e32 v118, v118, v22
	v_mul_f32_e32 v119, v119, v23
	v_mov_b32_dpp v120, v112 quad_perm:[1,0,3,2] row_mask:0xf bank_mask:0xf
	v_mov_b32_dpp v121, v113 quad_perm:[1,0,3,2] row_mask:0xf bank_mask:0xf
	v_mov_b32_dpp v122, v114 quad_perm:[1,0,3,2] row_mask:0xf bank_mask:0xf
	v_mov_b32_dpp v123, v115 quad_perm:[1,0,3,2] row_mask:0xf bank_mask:0xf
	v_mov_b32_dpp v124, v116 quad_perm:[1,0,3,2] row_mask:0xf bank_mask:0xf
	v_mov_b32_dpp v125, v117 quad_perm:[1,0,3,2] row_mask:0xf bank_mask:0xf
	v_mov_b32_dpp v126, v118 quad_perm:[1,0,3,2] row_mask:0xf bank_mask:0xf
	v_mov_b32_dpp v127, v119 quad_perm:[1,0,3,2] row_mask:0xf bank_mask:0xf
	v_mul_f32_e32 v128, s28, v112
	v_mul_f32_e32 v129, s29, v113
	v_mul_f32_e32 v130, s30, v114
	v_mul_f32_e32 v131, s31, v115
	v_mul_f32_e32 v132, s34, v116
	v_mul_f32_e32 v133, s35, v117
	v_mul_f32_e32 v134, s36, v118
	v_mul_f32_e32 v135, s37, v119
	v_fmac_f32_e32 v128, v32, v120
	v_fmac_f32_e32 v129, v33, v121
	v_fmac_f32_e32 v130, v34, v122
	v_fmac_f32_e32 v131, v35, v123
	v_fmac_f32_e32 v132, v36, v124
	v_fmac_f32_e32 v133, v37, v125
	v_fmac_f32_e32 v134, v38, v126
	v_fmac_f32_e32 v135, v39, v127
	v_cndmask_b32_e32 v112, v112, v128, vcc
	v_cndmask_b32_e32 v113, v113, v129, vcc
	v_cndmask_b32_e32 v114, v114, v130, vcc
	v_cndmask_b32_e32 v115, v115, v131, vcc
	v_cndmask_b32_e32 v116, v116, v132, vcc
	v_cndmask_b32_e32 v117, v117, v133, vcc
	v_cndmask_b32_e32 v118, v118, v134, vcc
	v_cndmask_b32_e32 v119, v119, v135, vcc
	v_mul_f32_e32 v112, 0x3e38aa3b, v112
	v_mul_f32_e32 v113, 0x3e38aa3b, v113
	v_mul_f32_e32 v114, 0x3e38aa3b, v114
	v_mul_f32_e32 v115, 0x3e38aa3b, v115
	v_mul_f32_e32 v116, 0x3e38aa3b, v116
	v_mul_f32_e32 v117, 0x3e38aa3b, v117
	v_mul_f32_e32 v118, 0x3e38aa3b, v118
	v_mul_f32_e32 v119, 0x3e38aa3b, v119
	v_cvt_pk_bf16_f32 v136, v112, v113
	v_cvt_pk_bf16_f32 v137, v114, v115
	v_cvt_pk_bf16_f32 v138, v116, v117
	v_cvt_pk_bf16_f32 v139, v118, v119
	global_store_dwordx4 v7, v[136:139], s[6:7]
	s_nop 1
	v_lshlrev_b32_e32 v112, 16, v108
	v_and_b32_e32 v113, 0xffff0000, v108
	v_lshlrev_b32_e32 v114, 16, v109
	v_and_b32_e32 v115, 0xffff0000, v109
	v_lshlrev_b32_e32 v116, 16, v110
	v_and_b32_e32 v117, 0xffff0000, v110
	v_lshlrev_b32_e32 v118, 16, v111
	v_and_b32_e32 v119, 0xffff0000, v111
	v_mul_f32_e32 v140, v112, v112
	v_mul_f32_e32 v141, v113, v113
	v_fmac_f32_e32 v140, v114, v114
	v_fmac_f32_e32 v141, v115, v115
	v_fmac_f32_e32 v140, v116, v116
	v_fmac_f32_e32 v141, v117, v117
	v_fmac_f32_e32 v140, v118, v118
	v_fmac_f32_e32 v141, v119, v119
	v_add_f32_e32 v140, v140, v141
	s_nop 1
	v_add_f32_dpp v140, v140, v140 quad_perm:[1,0,3,2] row_mask:0xf bank_mask:0xf bound_ctrl:1
	s_nop 1
	v_add_f32_dpp v140, v140, v140 quad_perm:[2,3,0,1] row_mask:0xf bank_mask:0xf bound_ctrl:1
	s_nop 1
	v_add_f32_dpp v140, v140, v140 row_half_mirror row_mask:0xf bank_mask:0xf bound_ctrl:1
	v_fma_f32 v141, v140, s10, v15
	v_rsq_f32_e32 v141, v141
	s_nop 0
	v_mul_f32_e32 v112, v112, v141
	v_mul_f32_e32 v113, v113, v141
	v_mul_f32_e32 v114, v114, v141
	v_mul_f32_e32 v115, v115, v141
	v_mul_f32_e32 v116, v116, v141
	v_mul_f32_e32 v117, v117, v141
	v_mul_f32_e32 v118, v118, v141
	v_mul_f32_e32 v119, v119, v141
	v_mul_f32_e32 v112, v112, v24
	v_mul_f32_e32 v113, v113, v25
	v_mul_f32_e32 v114, v114, v26
	v_mul_f32_e32 v115, v115, v27
	v_mul_f32_e32 v116, v116, v28
	v_mul_f32_e32 v117, v117, v29
	v_mul_f32_e32 v118, v118, v30
	v_mul_f32_e32 v119, v119, v31
	v_mov_b32_dpp v120, v112 quad_perm:[1,0,3,2] row_mask:0xf bank_mask:0xf
	v_mov_b32_dpp v121, v113 quad_perm:[1,0,3,2] row_mask:0xf bank_mask:0xf
	v_mov_b32_dpp v122, v114 quad_perm:[1,0,3,2] row_mask:0xf bank_mask:0xf
	v_mov_b32_dpp v123, v115 quad_perm:[1,0,3,2] row_mask:0xf bank_mask:0xf
	v_mov_b32_dpp v124, v116 quad_perm:[1,0,3,2] row_mask:0xf bank_mask:0xf
	v_mov_b32_dpp v125, v117 quad_perm:[1,0,3,2] row_mask:0xf bank_mask:0xf
	v_mov_b32_dpp v126, v118 quad_perm:[1,0,3,2] row_mask:0xf bank_mask:0xf
	v_mov_b32_dpp v127, v119 quad_perm:[1,0,3,2] row_mask:0xf bank_mask:0xf
	v_mul_f32_e32 v128, s28, v112
	v_mul_f32_e32 v129, s29, v113
	v_mul_f32_e32 v130, s30, v114
	v_mul_f32_e32 v131, s31, v115
	v_mul_f32_e32 v132, s34, v116
	v_mul_f32_e32 v133, s35, v117
	v_mul_f32_e32 v134, s36, v118
	v_mul_f32_e32 v135, s37, v119
	v_fmac_f32_e32 v128, v32, v120
	v_fmac_f32_e32 v129, v33, v121
	v_fmac_f32_e32 v130, v34, v122
	v_fmac_f32_e32 v131, v35, v123
	v_fmac_f32_e32 v132, v36, v124
	v_fmac_f32_e32 v133, v37, v125
	v_fmac_f32_e32 v134, v38, v126
	v_fmac_f32_e32 v135, v39, v127
	v_cndmask_b32_e32 v112, v112, v128, vcc
	v_cndmask_b32_e32 v113, v113, v129, vcc
	v_cndmask_b32_e32 v114, v114, v130, vcc
	v_cndmask_b32_e32 v115, v115, v131, vcc
	v_cndmask_b32_e32 v116, v116, v132, vcc
	v_cndmask_b32_e32 v117, v117, v133, vcc
	v_cndmask_b32_e32 v118, v118, v134, vcc
	v_cndmask_b32_e32 v119, v119, v135, vcc
	v_cvt_pk_bf16_f32 v136, v112, v113
	v_cvt_pk_bf16_f32 v137, v114, v115
	v_cvt_pk_bf16_f32 v138, v116, v117
	v_cvt_pk_bf16_f32 v139, v118, v119
	v_cndmask_b32_e64 v136, v136, v108, s[18:19]
	v_cndmask_b32_e64 v137, v137, v109, s[18:19]
	v_cndmask_b32_e64 v138, v138, v110, s[18:19]
	v_cndmask_b32_e64 v139, v139, v111, s[18:19]
	global_store_dwordx4 v8, v[136:139], s[12:13]
	s_add_u32 s6, s6, 0x200000
	s_addc_u32 s7, s7, 0
	s_add_u32 s12, s12, 0x80000
	s_addc_u32 s13, s13, 0
	s_branch .LBB0_278
	s_nop 0
	s_nop 0
	s_nop 0
	s_nop 0
	s_nop 0
	s_nop 0
	s_nop 0
	s_nop 0
	s_nop 0
	s_nop 0
	s_nop 0
	s_nop 0
	s_nop 0
	s_nop 0
	s_nop 0
	s_nop 0
	s_nop 0
	s_nop 0
	s_nop 0
	s_nop 0
	s_nop 0
	s_nop 0
	s_nop 0
	s_nop 0
	s_nop 0
	s_nop 0
	s_nop 0
	s_nop 0
	s_nop 0
	s_nop 0
	s_nop 0
	s_nop 0
	s_nop 0
	s_nop 0
	s_nop 0
	s_nop 0
	s_nop 0
	s_nop 0
	s_nop 0
	s_nop 0
	s_nop 0
	s_nop 0
	s_nop 0
	s_nop 0
	s_nop 0
	s_nop 0
	s_nop 0
	s_nop 0
	s_nop 0
	s_nop 0
	s_nop 0
	s_nop 0
	s_nop 0
	s_nop 0
	s_nop 0
	s_nop 0
	s_nop 0
	s_nop 0
	s_nop 0
	s_nop 0
	s_nop 0
	s_nop 0
	s_nop 0
	s_nop 0
	s_nop 0
	s_nop 0
	s_nop 0
	s_nop 0
	s_nop 0
	s_nop 0
	s_nop 0
	s_nop 0
	s_nop 0
	s_nop 0
	s_nop 0
	s_nop 0
	s_nop 0
	s_nop 0
	s_nop 0
	s_nop 0
	s_nop 0
	s_nop 0
	s_nop 0
	s_nop 0
	s_nop 0
	s_nop 0
	s_nop 0
	s_nop 0
	s_nop 0
	s_nop 0
	s_nop 0
	s_nop 0
	s_nop 0
	s_nop 0
	s_nop 0
	s_nop 0
	s_nop 0
	s_nop 0
	s_nop 0
	s_nop 0
	s_nop 0
	s_nop 0
	s_nop 0
	s_nop 0
	s_nop 0
	s_nop 0
	s_nop 0
	s_nop 0
	s_nop 0
	s_nop 0
	s_nop 0
	s_nop 0
	s_nop 0
	s_nop 0
	s_nop 0
	s_nop 0
	s_nop 0
	s_nop 0
	s_nop 0
	s_nop 0
	s_nop 0
	s_nop 0
	s_nop 0
	s_nop 0
	s_nop 0
	s_nop 0
	s_nop 0
	s_nop 0
	s_nop 0
	s_nop 0
	s_nop 0
	s_nop 0
	s_nop 0
	s_nop 0
	s_nop 0
	s_nop 0
	s_nop 0
	s_nop 0
	s_nop 0
	s_nop 0
	s_nop 0
	s_nop 0
	s_nop 0
	s_nop 0
	s_nop 0
	s_nop 0
	s_nop 0
	s_nop 0
	s_nop 0
	s_nop 0
	s_nop 0
	s_nop 0
	s_nop 0
	s_nop 0
	s_nop 0
	s_nop 0
	s_nop 0
	s_nop 0
	s_nop 0
	s_nop 0
	s_nop 0
	s_nop 0
	s_nop 0
	s_nop 0
	s_nop 0
	s_nop 0
	s_nop 0
	s_nop 0
	s_nop 0
	s_nop 0
	s_nop 0
	s_nop 0
	s_nop 0
	s_nop 0
	s_nop 0
	s_nop 0
	s_nop 0
	s_nop 0
	s_nop 0
	s_nop 0
	s_nop 0
	s_nop 0
	s_nop 0
	s_nop 0
	s_nop 0
	s_nop 0
	s_nop 0
	s_nop 0
	s_nop 0
	s_nop 0
	s_nop 0
	s_nop 0
	s_nop 0
	s_nop 0
	s_nop 0
	s_nop 0
	s_nop 0
	s_nop 0
	s_nop 0
	s_nop 0
	s_nop 0
	s_nop 0
	s_nop 0
	s_nop 0
	s_nop 0
	s_nop 0
	s_nop 0
	s_nop 0
	s_nop 0
	s_nop 0
	s_nop 0
	s_nop 0
	s_nop 0
	s_nop 0
	s_nop 0
	s_nop 0
	s_nop 0
	s_nop 0
	s_nop 0
	s_nop 0
	s_nop 0
	s_nop 0
	s_nop 0
	s_nop 0
	s_nop 0
	s_nop 0
	s_nop 0
	s_nop 0
	s_nop 0
	s_nop 0
	s_nop 0
	s_nop 0
	s_nop 0
	s_nop 0
	s_nop 0
	s_nop 0
	s_nop 0
	s_nop 0
	s_nop 0
	s_nop 0
	s_nop 0
	s_nop 0
	s_nop 0
	s_nop 0
	s_nop 0
	s_nop 0
	s_nop 0
	s_nop 0
	s_nop 0
	s_nop 0
	s_nop 0
	s_nop 0
	s_nop 0
	s_nop 0
	s_nop 0
	s_nop 0
	s_nop 0
	s_nop 0
	s_nop 0
	s_nop 0
	s_nop 0
	s_nop 0
	s_nop 0
	s_nop 0
	s_nop 0
	s_nop 0
	s_nop 0
	s_nop 0
	s_nop 0
	s_nop 0
	s_nop 0
	s_nop 0
	s_nop 0
	s_nop 0
	s_nop 0
	s_nop 0
	s_nop 0
	s_nop 0
	s_nop 0
	s_nop 0
	s_nop 0
	s_nop 0
	s_nop 0
	s_nop 0
	s_nop 0
	s_nop 0
	s_nop 0
	s_nop 0
	s_nop 0
	s_nop 0
	s_nop 0
	s_nop 0
	s_nop 0
	s_nop 0
	s_nop 0
	s_nop 0
	s_nop 0
	s_nop 0
	s_nop 0
	s_nop 0
	s_nop 0
	s_nop 0
	s_nop 0
	s_nop 0
	s_nop 0
	s_nop 0
	s_nop 0
	s_nop 0
	s_nop 0
	s_nop 0
	s_nop 0
	s_nop 0
	s_nop 0
	s_nop 0
	s_nop 0
	s_nop 0
	s_nop 0
	s_nop 0
	s_nop 0
	s_nop 0
